# combo16 + first K-loop iteration of each tile peeled with C = 0 on every accumulator's first MFMA; per-tile accumulator clears removed (gate/up, down, w_in loops)
# speedup vs baseline: 1.0080x; 1.0011x over previous
; #define PG8_STAGE(bufoff, gbase, voff) do { _Pragma("unroll") for (int _i = 0; _i < 2; ++_i) \
;         __builtin_amdgcn_global_load_lds((const unsigned*)((const char*)(gbase) + (voff)[_i]), (LAS unsigned*)(lds + (bufoff) + ldsw + _i * 8192), 16, 0, 0); } while (0)
; #define PG8_LDA(dst, b, h) do { _Pragma("unroll") for (int m = 0; m < 4; ++m) _Pragma("unroll") for (int k = 0; k < 2; ++k) dst[m][k] = *(const LAS bf16x8*)(lds + PG8_SA(b, h) + aoff + m * 2048 + k * 1024); } while (0)
; #define PG8_LDB(dst, b, h) do { _Pragma("unroll") for (int n = 0; n < 2; ++n) _Pragma("unroll") for (int k = 0; k < 2; ++k) dst[n][k] = *(const LAS bf16x8*)(lds + PG8_SB(b, h) + boff + n * 2048 + k * 1024); } while (0)
; #define PG8_MMA(ai, bj, At, Bt) do { __builtin_amdgcn_s_setprio(1); _Pragma("unroll") for (int m = 0; m < 4; ++m) _Pragma("unroll") for (int n = 0; n < 2; ++n) _Pragma("unroll") for (int k = 0; k < 2; ++k) \
;         acc[ai][bj][m][n] = __builtin_amdgcn_mfma_f32_16x16x32_bf16(Bt[n][k], At[m][k], acc[ai][bj][m][n], 0, 0, 0); __builtin_amdgcn_s_setprio(0); } while (0)
; #define PG8_WAIT_V(n) asm volatile("s_waitcnt vmcnt(" #n ")" ::: "memory")
; #define PG8_WAIT_L(n) asm volatile("s_waitcnt lgkmcnt(" #n ")" ::: "memory")
; #define PG8_BAR __builtin_amdgcn_s_barrier()
; #define PG8_SCHED __builtin_amdgcn_sched_barrier(0)
; template <class Epi>
; __device__ __forceinline__ void gemm_phase(LAS unsigned char* lds, const Gemm g, const StaticOrder& S, const Epi& E, const int tid) {
;     ...
;             PG8_LDB(B0, 0, 0); PG8_LDB(B1, 0, 1); PG8_SCHED; PG8_LDA(At, 0, 0); PG8_STAGE(PG8_SA(1, 1), a1 + hsA, voffA);
;             PG8_WAIT_V(8); PG8_WAIT_L(0); PG8_BAR; PG8_MMA(0, 0, At, B0); PG8_MMA(0, 1, At, B1); PG8_BAR; PG8_SCHED;
;             PG8_LDA(At, 0, 1); PG8_STAGE(PG8_SB(0, 0), b2, voffB); PG8_STAGE(PG8_SB(0, 1), b2 + hsB, voffB); PG8_STAGE(PG8_SA(0, 0), a2, voffA);
;     ...
;                 for (int m = 0; m < 4; ++m)
; #pragma unroll
;                     for (int n = 0; n < 2; ++n) acc[a][b][m][n] = (f32x4){0.f, 0.f, 0.f, 0.f};
.LBB0_160:
	s_ashr_i32 s15, s14, 31
	s_lshl_b64 s[16:17], s[14:15], 20
	s_add_u32 s16, s58, s16
	s_addc_u32 s17, s59, s17
	s_and_b64 s[18:19], s[36:37], exec
	s_cselect_b32 s15, s17, s35
	s_cselect_b32 s53, s16, s34
	s_ashr_i32 s13, s12, 31
	s_lshl_b64 s[18:19], s[12:13], 20
	s_add_u32 s18, s40, s18
	s_addc_u32 s19, s41, s19
	s_and_b64 s[38:39], s[36:37], exec
	s_cselect_b32 s13, s19, s1
	s_cselect_b32 s56, s18, s0
	s_add_u32 s34, s34, 0x80080
	s_addc_u32 s35, s35, 0
	s_add_u32 s57, s0, 0x100
	s_addc_u32 s58, s1, 0
	s_mov_b32 s59, -2
	s_cmp_lg_u64 s[10:11], 0
	s_cbranch_scc0 .Lgprio_a
	s_setprio 1
.Lgprio_a:
	s_add_u32 s0, s34, 0xfff80080
	s_addc_u32 s1, s35, -1
	s_add_i32 s24, 0, 0x10000
	s_cmp_eq_u32 s59, 28
	s_cselect_b32 s39, s15, s1
	s_cselect_b32 s38, s53, s0
	s_cselect_b32 s1, s13, s58
	s_cselect_b32 s0, s56, s57
	s_add_i32 s25, 0, 0x14000
	v_add_u32_e32 v154, s24, v143
	v_add_u32_e32 v166, s25, v143
	ds_read_b128 v[138:141], v154
	ds_read_b128 v[146:149], v154 offset:1024
	ds_read_b128 v[150:153], v154 offset:2048
	ds_read_b128 v[154:157], v154 offset:3072
	ds_read_b128 v[158:161], v166
	ds_read_b128 v[162:165], v166 offset:1024
	ds_read_b128 v[184:187], v166 offset:2048
	ds_read_b128 v[188:191], v166 offset:3072
	v_lshl_add_u64 v[166:167], s[34:35], 0, v[134:135]
	s_add_i32 m0, s42, 0xc000
	ds_read_b128 v[192:195], v145
	ds_read_b128 v[196:199], v145 offset:1024
	ds_read_b128 v[200:203], v145 offset:2048
	ds_read_b128 v[204:207], v145 offset:3072
	ds_read_b128 v[208:211], v145 offset:4096
	ds_read_b128 v[230:233], v145 offset:5120
	ds_read_b128 v[234:237], v145 offset:6144
	ds_read_b128 v[238:241], v145 offset:7168
	global_load_lds_dwordx4 v[166:167], off
	v_lshl_add_u64 v[166:167], s[34:35], 0, v[136:137]
	s_add_i32 m0, s42, 0xe000
	s_nop 0
	global_load_lds_dwordx4 v[166:167], off
	s_waitcnt vmcnt(8)
	s_waitcnt lgkmcnt(0)
	s_barrier
	v_mfma_f32_16x16x32_bf16 v[124:127], v[138:141], v[192:195], 0
	v_mfma_f32_16x16x32_bf16 v[116:119], v[150:153], v[192:195], 0
	v_mfma_f32_16x16x32_bf16 v[108:111], v[138:141], v[200:203], 0
	v_mfma_f32_16x16x32_bf16 v[100:103], v[150:153], v[200:203], 0
	v_mfma_f32_16x16x32_bf16 v[92:95], v[138:141], v[208:211], 0
	v_mfma_f32_16x16x32_bf16 v[84:87], v[150:153], v[208:211], 0
	v_mfma_f32_16x16x32_bf16 v[76:79], v[138:141], v[234:237], 0
	v_mfma_f32_16x16x32_bf16 v[68:71], v[150:153], v[234:237], 0
	v_mfma_f32_16x16x32_bf16 v[124:127], v[146:149], v[196:199], v[124:127]
	v_mfma_f32_16x16x32_bf16 v[116:119], v[154:157], v[196:199], v[116:119]
	v_mfma_f32_16x16x32_bf16 v[108:111], v[146:149], v[204:207], v[108:111]
	v_mfma_f32_16x16x32_bf16 v[100:103], v[154:157], v[204:207], v[100:103]
	v_mfma_f32_16x16x32_bf16 v[92:95], v[146:149], v[230:233], v[92:95]
	v_mfma_f32_16x16x32_bf16 v[84:87], v[154:157], v[230:233], v[84:87]
	v_mfma_f32_16x16x32_bf16 v[76:79], v[146:149], v[238:241], v[76:79]
	v_mfma_f32_16x16x32_bf16 v[68:71], v[154:157], v[238:241], v[68:71]
	v_mfma_f32_16x16x32_bf16 v[120:123], v[158:161], v[192:195], 0
	v_mfma_f32_16x16x32_bf16 v[112:115], v[184:187], v[192:195], 0
	v_mfma_f32_16x16x32_bf16 v[104:107], v[158:161], v[200:203], 0
	v_mfma_f32_16x16x32_bf16 v[96:99], v[184:187], v[200:203], 0
	v_mfma_f32_16x16x32_bf16 v[88:91], v[158:161], v[208:211], 0
	v_mfma_f32_16x16x32_bf16 v[80:83], v[184:187], v[208:211], 0
	v_mfma_f32_16x16x32_bf16 v[72:75], v[158:161], v[234:237], 0
	v_mfma_f32_16x16x32_bf16 v[64:67], v[184:187], v[234:237], 0
	v_mfma_f32_16x16x32_bf16 v[120:123], v[162:165], v[196:199], v[120:123]
	v_mfma_f32_16x16x32_bf16 v[112:115], v[188:191], v[196:199], v[112:115]
	v_mfma_f32_16x16x32_bf16 v[104:107], v[162:165], v[204:207], v[104:107]
	v_mfma_f32_16x16x32_bf16 v[96:99], v[188:191], v[204:207], v[96:99]
	v_mfma_f32_16x16x32_bf16 v[88:91], v[162:165], v[230:233], v[88:91]
	v_mfma_f32_16x16x32_bf16 v[80:83], v[188:191], v[230:233], v[80:83]
	v_mfma_f32_16x16x32_bf16 v[72:75], v[162:165], v[238:241], v[72:75]
	v_mfma_f32_16x16x32_bf16 v[64:67], v[188:191], v[238:241], v[64:67]
	s_barrier
	s_add_i32 s24, s24, s27
	v_lshl_add_u64 v[166:167], s[0:1], 0, v[168:169]
	s_mov_b32 m0, s24
	ds_read_b128 v[192:195], v145 offset:16384
	ds_read_b128 v[196:199], v145 offset:17408
	ds_read_b128 v[200:203], v145 offset:18432
	ds_read_b128 v[204:207], v145 offset:19456
	ds_read_b128 v[208:211], v145 offset:20480
	ds_read_b128 v[230:233], v145 offset:21504
	ds_read_b128 v[234:237], v145 offset:22528
	ds_read_b128 v[238:241], v145 offset:23552
	global_load_lds_dwordx4 v[166:167], off
	s_add_i32 m0, s24, 0x2000
	s_add_u32 s68, s0, 0x80000
	v_lshl_add_u64 v[212:213], s[0:1], 0, v[132:133]
	s_addc_u32 s69, s1, 0
	s_add_i32 s24, s25, s27
	global_load_lds_dwordx4 v[212:213], off
	v_lshl_add_u64 v[242:243], s[68:69], 0, v[168:169]
	s_mov_b32 m0, s24
	v_lshl_add_u64 v[244:245], s[38:39], 0, v[130:131]
	global_load_lds_dwordx4 v[242:243], off
	v_lshl_add_u64 v[242:243], s[68:69], 0, v[132:133]
	s_add_i32 m0, s24, 0x2000
	s_nop 0
	global_load_lds_dwordx4 v[242:243], off
	v_lshl_add_u64 v[242:243], s[38:39], 0, v[128:129]
	s_mov_b32 m0, s42
	s_nop 0
	global_load_lds_dwordx4 v[242:243], off
	s_mov_b32 m0, s43
	s_nop 0
	global_load_lds_dwordx4 v[244:245], off
	s_waitcnt vmcnt(8)
	s_waitcnt lgkmcnt(0)
	s_barrier
; #define PG8_STAGE(bufoff, gbase, voff) do { _Pragma("unroll") for (int _i = 0; _i < 2; ++_i) \
;         __builtin_amdgcn_global_load_lds((const unsigned*)((const char*)(gbase) + (voff)[_i]), (LAS unsigned*)(lds + (bufoff) + ldsw + _i * 8192), 16, 0, 0); } while (0)
; #define PG8_LDA(dst, b, h) do { _Pragma("unroll") for (int m = 0; m < 4; ++m) _Pragma("unroll") for (int k = 0; k < 2; ++k) dst[m][k] = *(const LAS bf16x8*)(lds + PG8_SA(b, h) + aoff + m * 2048 + k * 1024); } while (0)
; #define PG8_LDB(dst, b, h) do { _Pragma("unroll") for (int n = 0; n < 2; ++n) _Pragma("unroll") for (int k = 0; k < 2; ++k) dst[n][k] = *(const LAS bf16x8*)(lds + PG8_SB(b, h) + boff + n * 2048 + k * 1024); } while (0)
; #define PG8_MMA(ai, bj, At, Bt) do { __builtin_amdgcn_s_setprio(1); _Pragma("unroll") for (int m = 0; m < 4; ++m) _Pragma("unroll") for (int n = 0; n < 2; ++n) _Pragma("unroll") for (int k = 0; k < 2; ++k) \
;         acc[ai][bj][m][n] = __builtin_amdgcn_mfma_f32_16x16x32_bf16(Bt[n][k], At[m][k], acc[ai][bj][m][n], 0, 0, 0); __builtin_amdgcn_s_setprio(0); } while (0)
; #define PG8_WAIT_V(n) asm volatile("s_waitcnt vmcnt(" #n ")" ::: "memory")
; #define PG8_WAIT_L(n) asm volatile("s_waitcnt lgkmcnt(" #n ")" ::: "memory")
; #define PG8_BAR __builtin_amdgcn_s_barrier()
; #define PG8_SCHED __builtin_amdgcn_sched_barrier(0)
; template <class Epi>
; __device__ __forceinline__ void gemm_phase(LAS unsigned char* lds, const Gemm g, const StaticOrder& S, const Epi& E, const int tid) {
;     ...
;             PG8_WAIT_V(8); PG8_WAIT_L(0); PG8_BAR; PG8_MMA(1, 0, At, B0); PG8_MMA(1, 1, At, B1); PG8_BAR; PG8_SCHED;
;             PG8_LDB(B0, 1, 0); PG8_LDB(B1, 1, 1); PG8_SCHED; PG8_LDA(At, 1, 0); PG8_STAGE(PG8_SA(0, 1), a2 + hsA, voffA);
;             PG8_WAIT_V(8); PG8_WAIT_L(0); PG8_BAR; PG8_MMA(0, 0, At, B0); PG8_MMA(0, 1, At, B1); PG8_BAR; PG8_SCHED;
	v_mfma_f32_16x16x32_bf16 v[60:63], v[138:141], v[192:195], 0
	v_mfma_f32_16x16x32_bf16 v[52:55], v[150:153], v[192:195], 0
	v_mfma_f32_16x16x32_bf16 v[44:47], v[138:141], v[200:203], 0
	v_mfma_f32_16x16x32_bf16 v[36:39], v[150:153], v[200:203], 0
	v_mfma_f32_16x16x32_bf16 v[28:31], v[138:141], v[208:211], 0
	v_mfma_f32_16x16x32_bf16 v[20:23], v[150:153], v[208:211], 0
	v_mfma_f32_16x16x32_bf16 v[12:15], v[138:141], v[234:237], 0
	v_mfma_f32_16x16x32_bf16 v[4:7], v[150:153], v[234:237], 0
	v_mfma_f32_16x16x32_bf16 v[60:63], v[146:149], v[196:199], v[60:63]
	v_mfma_f32_16x16x32_bf16 v[52:55], v[154:157], v[196:199], v[52:55]
	v_mfma_f32_16x16x32_bf16 v[44:47], v[146:149], v[204:207], v[44:47]
	v_mfma_f32_16x16x32_bf16 v[36:39], v[154:157], v[204:207], v[36:39]
	v_mfma_f32_16x16x32_bf16 v[28:31], v[146:149], v[230:233], v[28:31]
	v_mfma_f32_16x16x32_bf16 v[20:23], v[154:157], v[230:233], v[20:23]
	v_mfma_f32_16x16x32_bf16 v[12:15], v[146:149], v[238:241], v[12:15]
	v_mfma_f32_16x16x32_bf16 v[4:7], v[154:157], v[238:241], v[4:7]
	v_mfma_f32_16x16x32_bf16 v[56:59], v[158:161], v[192:195], 0
	v_mfma_f32_16x16x32_bf16 v[48:51], v[184:187], v[192:195], 0
	v_mfma_f32_16x16x32_bf16 v[40:43], v[158:161], v[200:203], 0
	v_mfma_f32_16x16x32_bf16 v[32:35], v[184:187], v[200:203], 0
	v_mfma_f32_16x16x32_bf16 v[24:27], v[158:161], v[208:211], 0
	v_mfma_f32_16x16x32_bf16 v[16:19], v[184:187], v[208:211], 0
	v_mfma_f32_16x16x32_bf16 v[8:11], v[158:161], v[234:237], 0
	v_mfma_f32_16x16x32_bf16 v[0:3], v[184:187], v[234:237], 0
	v_mfma_f32_16x16x32_bf16 v[56:59], v[162:165], v[196:199], v[56:59]
	v_mfma_f32_16x16x32_bf16 v[48:51], v[188:191], v[196:199], v[48:51]
	v_mfma_f32_16x16x32_bf16 v[40:43], v[162:165], v[204:207], v[40:43]
	v_mfma_f32_16x16x32_bf16 v[32:35], v[188:191], v[204:207], v[32:35]
	v_mfma_f32_16x16x32_bf16 v[24:27], v[162:165], v[230:233], v[24:27]
	v_mfma_f32_16x16x32_bf16 v[16:19], v[188:191], v[230:233], v[16:19]
	v_mfma_f32_16x16x32_bf16 v[8:11], v[162:165], v[238:241], v[8:11]
	v_mfma_f32_16x16x32_bf16 v[0:3], v[188:191], v[238:241], v[0:3]
	s_barrier
	s_add_i32 s24, 0, 0x18000
	s_add_i32 s25, 0, 0x1c000
	v_add_u32_e32 v154, s24, v143
	v_add_u32_e32 v170, s25, v143
	ds_read_b128 v[138:141], v154
	ds_read_b128 v[146:149], v154 offset:1024
	ds_read_b128 v[150:153], v154 offset:2048
	ds_read_b128 v[154:157], v154 offset:3072
	ds_read_b128 v[158:161], v170
	ds_read_b128 v[162:165], v170 offset:1024
	ds_read_b128 v[184:187], v170 offset:2048
	ds_read_b128 v[188:191], v170 offset:3072
	s_add_u32 s38, s38, 0x80000
	s_addc_u32 s39, s39, 0
	s_mov_b32 m0, s44
	v_lshl_add_u64 v[246:247], s[38:39], 0, v[128:129]
	ds_read_b128 v[192:195], v145 offset:32768
	ds_read_b128 v[196:199], v145 offset:33792
	ds_read_b128 v[200:203], v145 offset:34816
	ds_read_b128 v[204:207], v145 offset:35840
	ds_read_b128 v[208:211], v145 offset:36864
	ds_read_b128 v[230:233], v145 offset:37888
	ds_read_b128 v[234:237], v145 offset:38912
	ds_read_b128 v[238:241], v145 offset:39936
	global_load_lds_dwordx4 v[246:247], off
	v_lshl_add_u64 v[246:247], s[38:39], 0, v[130:131]
	s_mov_b32 m0, s45
	s_nop 0
	global_load_lds_dwordx4 v[246:247], off
	s_waitcnt vmcnt(8)
	s_waitcnt lgkmcnt(0)
	s_barrier
	v_mfma_f32_16x16x32_bf16 v[124:127], v[138:141], v[192:195], v[124:127]
	v_mfma_f32_16x16x32_bf16 v[116:119], v[150:153], v[192:195], v[116:119]
	v_mfma_f32_16x16x32_bf16 v[108:111], v[138:141], v[200:203], v[108:111]
	v_mfma_f32_16x16x32_bf16 v[100:103], v[150:153], v[200:203], v[100:103]
	v_mfma_f32_16x16x32_bf16 v[92:95], v[138:141], v[208:211], v[92:95]
	v_mfma_f32_16x16x32_bf16 v[84:87], v[150:153], v[208:211], v[84:87]
	v_mfma_f32_16x16x32_bf16 v[76:79], v[138:141], v[234:237], v[76:79]
	v_mfma_f32_16x16x32_bf16 v[68:71], v[150:153], v[234:237], v[68:71]
	v_mfma_f32_16x16x32_bf16 v[124:127], v[146:149], v[196:199], v[124:127]
	v_mfma_f32_16x16x32_bf16 v[116:119], v[154:157], v[196:199], v[116:119]
	v_mfma_f32_16x16x32_bf16 v[108:111], v[146:149], v[204:207], v[108:111]
	v_mfma_f32_16x16x32_bf16 v[100:103], v[154:157], v[204:207], v[100:103]
	v_mfma_f32_16x16x32_bf16 v[92:95], v[146:149], v[230:233], v[92:95]
	v_mfma_f32_16x16x32_bf16 v[84:87], v[154:157], v[230:233], v[84:87]
	v_mfma_f32_16x16x32_bf16 v[76:79], v[146:149], v[238:241], v[76:79]
	v_mfma_f32_16x16x32_bf16 v[68:71], v[154:157], v[238:241], v[68:71]
	v_mfma_f32_16x16x32_bf16 v[120:123], v[158:161], v[192:195], v[120:123]
	v_mfma_f32_16x16x32_bf16 v[112:115], v[184:187], v[192:195], v[112:115]
	v_mfma_f32_16x16x32_bf16 v[104:107], v[158:161], v[200:203], v[104:107]
	v_mfma_f32_16x16x32_bf16 v[96:99], v[184:187], v[200:203], v[96:99]
	v_mfma_f32_16x16x32_bf16 v[88:91], v[158:161], v[208:211], v[88:91]
	v_mfma_f32_16x16x32_bf16 v[80:83], v[184:187], v[208:211], v[80:83]
	v_mfma_f32_16x16x32_bf16 v[72:75], v[158:161], v[234:237], v[72:75]
	v_mfma_f32_16x16x32_bf16 v[64:67], v[184:187], v[234:237], v[64:67]
	v_mfma_f32_16x16x32_bf16 v[120:123], v[162:165], v[196:199], v[120:123]
	v_mfma_f32_16x16x32_bf16 v[112:115], v[188:191], v[196:199], v[112:115]
	v_mfma_f32_16x16x32_bf16 v[104:107], v[162:165], v[204:207], v[104:107]
	v_mfma_f32_16x16x32_bf16 v[96:99], v[188:191], v[204:207], v[96:99]
	v_mfma_f32_16x16x32_bf16 v[88:91], v[162:165], v[230:233], v[88:91]
	v_mfma_f32_16x16x32_bf16 v[80:83], v[188:191], v[230:233], v[80:83]
	v_mfma_f32_16x16x32_bf16 v[72:75], v[162:165], v[238:241], v[72:75]
	v_mfma_f32_16x16x32_bf16 v[64:67], v[188:191], v[238:241], v[64:67]
	s_barrier
; #define PG8_STAGE(bufoff, gbase, voff) do { _Pragma("unroll") for (int _i = 0; _i < 2; ++_i) \
;         __builtin_amdgcn_global_load_lds((const unsigned*)((const char*)(gbase) + (voff)[_i]), (LAS unsigned*)(lds + (bufoff) + ldsw + _i * 8192), 16, 0, 0); } while (0)
; #define PG8_LDA(dst, b, h) do { _Pragma("unroll") for (int m = 0; m < 4; ++m) _Pragma("unroll") for (int k = 0; k < 2; ++k) dst[m][k] = *(const LAS bf16x8*)(lds + PG8_SA(b, h) + aoff + m * 2048 + k * 1024); } while (0)
; #define PG8_MMA(ai, bj, At, Bt) do { __builtin_amdgcn_s_setprio(1); _Pragma("unroll") for (int m = 0; m < 4; ++m) _Pragma("unroll") for (int n = 0; n < 2; ++n) _Pragma("unroll") for (int k = 0; k < 2; ++k) \
;         acc[ai][bj][m][n] = __builtin_amdgcn_mfma_f32_16x16x32_bf16(Bt[n][k], At[m][k], acc[ai][bj][m][n], 0, 0, 0); __builtin_amdgcn_s_setprio(0); } while (0)
; #define PG8_WAIT_V(n) asm volatile("s_waitcnt vmcnt(" #n ")" ::: "memory")
; #define PG8_WAIT_L(n) asm volatile("s_waitcnt lgkmcnt(" #n ")" ::: "memory")
; #define PG8_BAR __builtin_amdgcn_s_barrier()
; #define PG8_SCHED __builtin_amdgcn_sched_barrier(0)
; template <class Epi>
; __device__ __forceinline__ void gemm_phase(LAS unsigned char* lds, const Gemm g, const StaticOrder& S, const Epi& E, const int tid) {
;     ...
;             PG8_LDA(At, 1, 1); PG8_STAGE(PG8_SB(1, 0), b3, voffB); PG8_STAGE(PG8_SB(1, 1), b3 + hsB, voffB); PG8_STAGE(PG8_SA(1, 0), a3, voffA);
;             PG8_WAIT_V(8); PG8_WAIT_L(0); PG8_BAR; PG8_MMA(1, 0, At, B0); PG8_MMA(1, 1, At, B1); PG8_BAR; PG8_SCHED;
	s_add_i32 s24, s24, s27
	v_lshl_add_u64 v[166:167], v[166:167], 0, s[28:29]
	s_mov_b32 m0, s24
	ds_read_b128 v[192:195], v145 offset:49152
	ds_read_b128 v[196:199], v145 offset:50176
	ds_read_b128 v[200:203], v145 offset:51200
	ds_read_b128 v[204:207], v145 offset:52224
	ds_read_b128 v[208:211], v145 offset:53248
	ds_read_b128 v[230:233], v145 offset:54272
	ds_read_b128 v[234:237], v145 offset:55296
	ds_read_b128 v[238:241], v145 offset:56320
	global_load_lds_dwordx4 v[166:167], off
	s_add_i32 m0, s24, 0x2000
	s_add_u32 s0, s0, 0x80080
	v_lshl_add_u64 v[166:167], v[212:213], 0, s[28:29]
	s_addc_u32 s1, s1, 0
	s_add_i32 s24, s25, s27
	global_load_lds_dwordx4 v[166:167], off
	v_lshl_add_u64 v[166:167], s[0:1], 0, v[168:169]
	s_mov_b32 m0, s24
	s_nop 0
	global_load_lds_dwordx4 v[166:167], off
	v_lshl_add_u64 v[166:167], s[0:1], 0, v[132:133]
	s_add_i32 m0, s24, 0x2000
	s_nop 0
	global_load_lds_dwordx4 v[166:167], off
	v_lshl_add_u64 v[166:167], v[242:243], 0, s[28:29]
	s_mov_b32 m0, s46
	s_nop 0
	global_load_lds_dwordx4 v[166:167], off
	v_lshl_add_u64 v[166:167], v[244:245], 0, s[28:29]
	s_mov_b32 m0, s47
	s_nop 0
	global_load_lds_dwordx4 v[166:167], off
	s_waitcnt vmcnt(8)
	s_waitcnt lgkmcnt(0)
	s_barrier
	v_mfma_f32_16x16x32_bf16 v[60:63], v[138:141], v[192:195], v[60:63]
	v_mfma_f32_16x16x32_bf16 v[52:55], v[150:153], v[192:195], v[52:55]
	v_mfma_f32_16x16x32_bf16 v[44:47], v[138:141], v[200:203], v[44:47]
	v_mfma_f32_16x16x32_bf16 v[36:39], v[150:153], v[200:203], v[36:39]
	v_mfma_f32_16x16x32_bf16 v[28:31], v[138:141], v[208:211], v[28:31]
	v_mfma_f32_16x16x32_bf16 v[20:23], v[150:153], v[208:211], v[20:23]
	v_mfma_f32_16x16x32_bf16 v[12:15], v[138:141], v[234:237], v[12:15]
	v_mfma_f32_16x16x32_bf16 v[4:7], v[150:153], v[234:237], v[4:7]
	v_mfma_f32_16x16x32_bf16 v[60:63], v[146:149], v[196:199], v[60:63]
	v_mfma_f32_16x16x32_bf16 v[52:55], v[154:157], v[196:199], v[52:55]
	v_mfma_f32_16x16x32_bf16 v[44:47], v[146:149], v[204:207], v[44:47]
	v_mfma_f32_16x16x32_bf16 v[36:39], v[154:157], v[204:207], v[36:39]
	v_mfma_f32_16x16x32_bf16 v[28:31], v[146:149], v[230:233], v[28:31]
	v_mfma_f32_16x16x32_bf16 v[20:23], v[154:157], v[230:233], v[20:23]
	v_mfma_f32_16x16x32_bf16 v[12:15], v[146:149], v[238:241], v[12:15]
	v_mfma_f32_16x16x32_bf16 v[4:7], v[154:157], v[238:241], v[4:7]
	v_mfma_f32_16x16x32_bf16 v[56:59], v[158:161], v[192:195], v[56:59]
	v_mfma_f32_16x16x32_bf16 v[48:51], v[184:187], v[192:195], v[48:51]
	v_mfma_f32_16x16x32_bf16 v[40:43], v[158:161], v[200:203], v[40:43]
	v_mfma_f32_16x16x32_bf16 v[32:35], v[184:187], v[200:203], v[32:35]
	v_mfma_f32_16x16x32_bf16 v[24:27], v[158:161], v[208:211], v[24:27]
	v_mfma_f32_16x16x32_bf16 v[16:19], v[184:187], v[208:211], v[16:19]
	v_mfma_f32_16x16x32_bf16 v[8:11], v[158:161], v[234:237], v[8:11]
	v_mfma_f32_16x16x32_bf16 v[0:3], v[184:187], v[234:237], v[0:3]
	v_mfma_f32_16x16x32_bf16 v[56:59], v[162:165], v[196:199], v[56:59]
	v_mfma_f32_16x16x32_bf16 v[48:51], v[188:191], v[196:199], v[48:51]
	v_mfma_f32_16x16x32_bf16 v[40:43], v[162:165], v[204:207], v[40:43]
	v_mfma_f32_16x16x32_bf16 v[32:35], v[188:191], v[204:207], v[32:35]
	v_mfma_f32_16x16x32_bf16 v[24:27], v[162:165], v[230:233], v[24:27]
	v_mfma_f32_16x16x32_bf16 v[16:19], v[188:191], v[230:233], v[16:19]
	v_mfma_f32_16x16x32_bf16 v[8:11], v[162:165], v[238:241], v[8:11]
	v_mfma_f32_16x16x32_bf16 v[0:3], v[188:191], v[238:241], v[0:3]
	s_barrier
	s_add_i32 s59, s59, 2
	s_add_u32 s34, s34, 0x100
	s_addc_u32 s35, s35, 0
	s_add_u32 s57, s57, 0x100
	s_addc_u32 s58, s58, 0
	s_cmp_gt_u32 s59, 29

; #define PG8_STAGE(bufoff, gbase, voff) do { _Pragma("unroll") for (int _i = 0; _i < 2; ++_i) \
;         __builtin_amdgcn_global_load_lds((const unsigned*)((const char*)(gbase) + (voff)[_i]), (LAS unsigned*)(lds + (bufoff) + ldsw + _i * 8192), 16, 0, 0); } while (0)
; #define PG8_LDA(dst, b, h) do { _Pragma("unroll") for (int m = 0; m < 4; ++m) _Pragma("unroll") for (int k = 0; k < 2; ++k) dst[m][k] = *(const LAS bf16x8*)(lds + PG8_SA(b, h) + aoff + m * 2048 + k * 1024); } while (0)
; #define PG8_LDB(dst, b, h) do { _Pragma("unroll") for (int n = 0; n < 2; ++n) _Pragma("unroll") for (int k = 0; k < 2; ++k) dst[n][k] = *(const LAS bf16x8*)(lds + PG8_SB(b, h) + boff + n * 2048 + k * 1024); } while (0)
; #define PG8_WAIT_V(n) asm volatile("s_waitcnt vmcnt(" #n ")" ::: "memory")
; #define PG8_WAIT_L(n) asm volatile("s_waitcnt lgkmcnt(" #n ")" ::: "memory")
; template <class Epi>
; __device__ __forceinline__ void gemm_phase(LAS unsigned char* lds, const Gemm g, const StaticOrder& S, const Epi& E, const int tid) {
;     ...
;         for (int t = 0; t < nt; t += 2) {
;             const bool last = (t == nt - 2);
;             const char* a1 = cA + (size_t)(t + 1) * kstep;
;             const char* a2 = last ? nA : cA + (size_t)(t + 2) * kstep; const char* b2 = last ? nB : cB + (size_t)(t + 2) * kstep;
;             const char* a3 = a2 + kstep; const char* b3 = b2 + kstep;
;             PG8_LDB(B0, 0, 0); PG8_LDB(B1, 0, 1); PG8_SCHED; PG8_LDA(At, 0, 0); PG8_STAGE(PG8_SA(1, 1), a1 + hsA, voffA);
;             PG8_WAIT_V(8); PG8_WAIT_L(0); PG8_BAR; PG8_MMA(0, 0, At, B0); PG8_MMA(0, 1, At, B1); PG8_BAR; PG8_SCHED;
;             PG8_LDA(At, 0, 1); PG8_STAGE(PG8_SB(0, 0), b2, voffB); PG8_STAGE(PG8_SB(0, 1), b2 + hsB, voffB); PG8_STAGE(PG8_SA(0, 0), a2, voffA);
;             PG8_WAIT_V(8); PG8_WAIT_L(0); PG8_BAR; PG8_MMA(1, 0, At, B0); PG8_MMA(1, 1, At, B1); PG8_BAR; PG8_SCHED;
;             PG8_LDB(B0, 1, 0); PG8_LDB(B1, 1, 1); PG8_SCHED; PG8_LDA(At, 1, 0); PG8_STAGE(PG8_SA(0, 1), a2 + hsA, voffA);
;             PG8_WAIT_V(8); PG8_WAIT_L(0); PG8_BAR; PG8_MMA(0, 0, At, B0); PG8_MMA(0, 1, At, B1); PG8_BAR; PG8_SCHED;
;             PG8_LDA(At, 1, 1); PG8_STAGE(PG8_SB(1, 0), b3, voffB); PG8_STAGE(PG8_SB(1, 1), b3 + hsB, voffB); PG8_STAGE(PG8_SA(1, 0), a3, voffA);
;             PG8_WAIT_V(8); PG8_WAIT_L(0); PG8_BAR; PG8_MMA(1, 0, At, B0); PG8_MMA(1, 1, At, B1); PG8_BAR; PG8_SCHED;
.LBB0_232:
	s_add_u32 s42, s0, 0x100
	s_addc_u32 s43, s1, 0
	s_mov_b32 s69, -2
	s_cmp_lg_u64 s[10:11], 0
	s_cbranch_scc0 .Lgprio_b
	s_setprio 1
.Lgprio_b:
	s_add_u32 s0, s18, 0x100
	s_addc_u32 s1, s19, 0
	s_add_i32 s24, 0, 0x10000
	s_cmpk_eq_i32 s69, 0x54
	s_cselect_b32 s37, s15, s1
	s_cselect_b32 s36, s14, s0
	s_cselect_b32 s35, s17, s43
	s_cselect_b32 s34, s16, s42
	s_add_i32 s25, 0, 0x14000
	v_add_u32_e32 v152, s24, v193
	v_add_u32_e32 v170, s25, v193
	ds_read_b128 v[128:131], v152
	ds_read_b128 v[132:135], v152 offset:1024
	ds_read_b128 v[136:139], v152 offset:2048
	ds_read_b128 v[152:155], v152 offset:3072
	ds_read_b128 v[156:159], v170
	ds_read_b128 v[160:163], v170 offset:1024
	ds_read_b128 v[164:167], v170 offset:2048
	ds_read_b128 v[184:187], v170 offset:3072
	v_lshl_add_u64 v[212:213], s[18:19], 0, v[148:149]
	s_add_i32 m0, s44, 0xc000
	ds_read_b128 v[188:191], v198
	ds_read_b128 v[200:203], v198 offset:1024
	ds_read_b128 v[204:207], v198 offset:2048
	ds_read_b128 v[208:211], v198 offset:3072
	ds_read_b128 v[230:233], v198 offset:4096
	ds_read_b128 v[234:237], v198 offset:5120
	ds_read_b128 v[238:241], v198 offset:6144
	ds_read_b128 v[242:245], v198 offset:7168
	global_load_lds_dwordx4 v[212:213], off
	v_lshl_add_u64 v[212:213], s[18:19], 0, v[150:151]
	s_add_i32 m0, s44, 0xe000
	s_nop 0
	global_load_lds_dwordx4 v[212:213], off
	s_waitcnt vmcnt(8)
	s_waitcnt lgkmcnt(0)
	s_barrier
	v_mfma_f32_16x16x32_bf16 v[124:127], v[128:131], v[188:191], 0
	v_mfma_f32_16x16x32_bf16 v[120:123], v[136:139], v[188:191], 0
	v_mfma_f32_16x16x32_bf16 v[116:119], v[128:131], v[204:207], 0
	v_mfma_f32_16x16x32_bf16 v[108:111], v[136:139], v[204:207], 0
	v_mfma_f32_16x16x32_bf16 v[92:95], v[128:131], v[230:233], 0
	v_mfma_f32_16x16x32_bf16 v[88:91], v[136:139], v[230:233], 0
	v_mfma_f32_16x16x32_bf16 v[80:83], v[128:131], v[238:241], 0
	v_mfma_f32_16x16x32_bf16 v[72:75], v[136:139], v[238:241], 0
	v_mfma_f32_16x16x32_bf16 v[124:127], v[132:135], v[200:203], v[124:127]
	v_mfma_f32_16x16x32_bf16 v[120:123], v[152:155], v[200:203], v[120:123]
	v_mfma_f32_16x16x32_bf16 v[116:119], v[132:135], v[208:211], v[116:119]
	v_mfma_f32_16x16x32_bf16 v[108:111], v[152:155], v[208:211], v[108:111]
	v_mfma_f32_16x16x32_bf16 v[92:95], v[132:135], v[234:237], v[92:95]
	v_mfma_f32_16x16x32_bf16 v[88:91], v[152:155], v[234:237], v[88:91]
	v_mfma_f32_16x16x32_bf16 v[80:83], v[132:135], v[242:245], v[80:83]
	v_mfma_f32_16x16x32_bf16 v[72:75], v[152:155], v[242:245], v[72:75]
	v_mfma_f32_16x16x32_bf16 v[112:115], v[156:159], v[188:191], 0
	v_mfma_f32_16x16x32_bf16 v[104:107], v[164:167], v[188:191], 0
	v_mfma_f32_16x16x32_bf16 v[100:103], v[156:159], v[204:207], 0
	v_mfma_f32_16x16x32_bf16 v[96:99], v[164:167], v[204:207], 0
	v_mfma_f32_16x16x32_bf16 v[84:87], v[156:159], v[230:233], 0
	v_mfma_f32_16x16x32_bf16 v[76:79], v[164:167], v[230:233], 0
	v_mfma_f32_16x16x32_bf16 v[68:71], v[156:159], v[238:241], 0
	v_mfma_f32_16x16x32_bf16 v[64:67], v[164:167], v[238:241], 0
	v_mfma_f32_16x16x32_bf16 v[112:115], v[160:163], v[200:203], v[112:115]
	v_mfma_f32_16x16x32_bf16 v[104:107], v[184:187], v[200:203], v[104:107]
	v_mfma_f32_16x16x32_bf16 v[100:103], v[160:163], v[208:211], v[100:103]
	v_mfma_f32_16x16x32_bf16 v[96:99], v[184:187], v[208:211], v[96:99]
	v_mfma_f32_16x16x32_bf16 v[84:87], v[160:163], v[234:237], v[84:87]
	v_mfma_f32_16x16x32_bf16 v[76:79], v[184:187], v[234:237], v[76:79]
	v_mfma_f32_16x16x32_bf16 v[68:71], v[160:163], v[242:245], v[68:71]
	v_mfma_f32_16x16x32_bf16 v[64:67], v[184:187], v[242:245], v[64:67]
	s_barrier
	s_add_i32 s18, s24, s39
	v_lshl_add_u64 v[212:213], s[34:35], 0, v[144:145]
	s_mov_b32 m0, s18
	ds_read_b128 v[188:191], v198 offset:16384
	ds_read_b128 v[200:203], v198 offset:17408
	ds_read_b128 v[204:207], v198 offset:18432
	ds_read_b128 v[208:211], v198 offset:19456
	ds_read_b128 v[230:233], v198 offset:20480
	ds_read_b128 v[234:237], v198 offset:21504
	ds_read_b128 v[238:241], v198 offset:22528
	ds_read_b128 v[242:245], v198 offset:23552
	global_load_lds_dwordx4 v[212:213], off
	s_add_i32 m0, s18, 0x2000
	s_add_u32 s18, s34, 0x160000
	v_lshl_add_u64 v[246:247], s[34:35], 0, v[140:141]
	s_addc_u32 s19, s35, 0
	s_add_i32 s24, s25, s39
	global_load_lds_dwordx4 v[246:247], off
	v_lshl_add_u64 v[248:249], s[18:19], 0, v[144:145]
	s_mov_b32 m0, s24
	v_lshl_add_u64 v[250:251], s[36:37], 0, v[142:143]
	global_load_lds_dwordx4 v[248:249], off
	v_lshl_add_u64 v[248:249], s[18:19], 0, v[140:141]
	s_add_i32 m0, s24, 0x2000
	s_nop 0
	global_load_lds_dwordx4 v[248:249], off
	v_lshl_add_u64 v[248:249], s[36:37], 0, v[146:147]
	s_mov_b32 m0, s44
	s_nop 0
	global_load_lds_dwordx4 v[248:249], off
	s_mov_b32 m0, s45
	s_nop 0
	global_load_lds_dwordx4 v[250:251], off
	s_waitcnt vmcnt(8)
	s_waitcnt lgkmcnt(0)
	s_barrier
; #define PG8_STAGE(bufoff, gbase, voff) do { _Pragma("unroll") for (int _i = 0; _i < 2; ++_i) \
;         __builtin_amdgcn_global_load_lds((const unsigned*)((const char*)(gbase) + (voff)[_i]), (LAS unsigned*)(lds + (bufoff) + ldsw + _i * 8192), 16, 0, 0); } while (0)
; #define PG8_LDA(dst, b, h) do { _Pragma("unroll") for (int m = 0; m < 4; ++m) _Pragma("unroll") for (int k = 0; k < 2; ++k) dst[m][k] = *(const LAS bf16x8*)(lds + PG8_SA(b, h) + aoff + m * 2048 + k * 1024); } while (0)
; #define PG8_LDB(dst, b, h) do { _Pragma("unroll") for (int n = 0; n < 2; ++n) _Pragma("unroll") for (int k = 0; k < 2; ++k) dst[n][k] = *(const LAS bf16x8*)(lds + PG8_SB(b, h) + boff + n * 2048 + k * 1024); } while (0)
; #define PG8_WAIT_V(n) asm volatile("s_waitcnt vmcnt(" #n ")" ::: "memory")
; #define PG8_WAIT_L(n) asm volatile("s_waitcnt lgkmcnt(" #n ")" ::: "memory")
; template <class Epi>
; __device__ __forceinline__ void gemm_phase(LAS unsigned char* lds, const Gemm g, const StaticOrder& S, const Epi& E, const int tid) {
;     ...
;         for (int t = 0; t < nt; t += 2) {
;             const bool last = (t == nt - 2);
;             const char* a1 = cA + (size_t)(t + 1) * kstep;
;             const char* a2 = last ? nA : cA + (size_t)(t + 2) * kstep; const char* b2 = last ? nB : cB + (size_t)(t + 2) * kstep;
;             const char* a3 = a2 + kstep; const char* b3 = b2 + kstep;
;             PG8_LDB(B0, 0, 0); PG8_LDB(B1, 0, 1); PG8_SCHED; PG8_LDA(At, 0, 0); PG8_STAGE(PG8_SA(1, 1), a1 + hsA, voffA);
;             PG8_WAIT_V(8); PG8_WAIT_L(0); PG8_BAR; PG8_MMA(0, 0, At, B0); PG8_MMA(0, 1, At, B1); PG8_BAR; PG8_SCHED;
;             PG8_LDA(At, 0, 1); PG8_STAGE(PG8_SB(0, 0), b2, voffB); PG8_STAGE(PG8_SB(0, 1), b2 + hsB, voffB); PG8_STAGE(PG8_SA(0, 0), a2, voffA);
;             PG8_WAIT_V(8); PG8_WAIT_L(0); PG8_BAR; PG8_MMA(1, 0, At, B0); PG8_MMA(1, 1, At, B1); PG8_BAR; PG8_SCHED;
;             PG8_LDB(B0, 1, 0); PG8_LDB(B1, 1, 1); PG8_SCHED; PG8_LDA(At, 1, 0); PG8_STAGE(PG8_SA(0, 1), a2 + hsA, voffA);
;             PG8_WAIT_V(8); PG8_WAIT_L(0); PG8_BAR; PG8_MMA(0, 0, At, B0); PG8_MMA(0, 1, At, B1); PG8_BAR; PG8_SCHED;
;             PG8_LDA(At, 1, 1); PG8_STAGE(PG8_SB(1, 0), b3, voffB); PG8_STAGE(PG8_SB(1, 1), b3 + hsB, voffB); PG8_STAGE(PG8_SA(1, 0), a3, voffA);
;             PG8_WAIT_V(8); PG8_WAIT_L(0); PG8_BAR; PG8_MMA(1, 0, At, B0); PG8_MMA(1, 1, At, B1); PG8_BAR; PG8_SCHED;
	v_mfma_f32_16x16x32_bf16 v[60:63], v[128:131], v[188:191], 0
	v_mfma_f32_16x16x32_bf16 v[56:59], v[136:139], v[188:191], 0
	v_mfma_f32_16x16x32_bf16 v[44:47], v[128:131], v[204:207], 0
	v_mfma_f32_16x16x32_bf16 v[40:43], v[136:139], v[204:207], 0
	v_mfma_f32_16x16x32_bf16 v[28:31], v[128:131], v[230:233], 0
	v_mfma_f32_16x16x32_bf16 v[24:27], v[136:139], v[230:233], 0
	v_mfma_f32_16x16x32_bf16 v[12:15], v[128:131], v[238:241], 0
	v_mfma_f32_16x16x32_bf16 v[8:11], v[136:139], v[238:241], 0
	v_mfma_f32_16x16x32_bf16 v[60:63], v[132:135], v[200:203], v[60:63]
	v_mfma_f32_16x16x32_bf16 v[56:59], v[152:155], v[200:203], v[56:59]
	v_mfma_f32_16x16x32_bf16 v[44:47], v[132:135], v[208:211], v[44:47]
	v_mfma_f32_16x16x32_bf16 v[40:43], v[152:155], v[208:211], v[40:43]
	v_mfma_f32_16x16x32_bf16 v[28:31], v[132:135], v[234:237], v[28:31]
	v_mfma_f32_16x16x32_bf16 v[24:27], v[152:155], v[234:237], v[24:27]
	v_mfma_f32_16x16x32_bf16 v[12:15], v[132:135], v[242:245], v[12:15]
	v_mfma_f32_16x16x32_bf16 v[8:11], v[152:155], v[242:245], v[8:11]
	v_mfma_f32_16x16x32_bf16 v[52:55], v[156:159], v[188:191], 0
	v_mfma_f32_16x16x32_bf16 v[48:51], v[164:167], v[188:191], 0
	v_mfma_f32_16x16x32_bf16 v[36:39], v[156:159], v[204:207], 0
	v_mfma_f32_16x16x32_bf16 v[32:35], v[164:167], v[204:207], 0
	v_mfma_f32_16x16x32_bf16 v[20:23], v[156:159], v[230:233], 0
	v_mfma_f32_16x16x32_bf16 v[16:19], v[164:167], v[230:233], 0
	v_mfma_f32_16x16x32_bf16 v[4:7], v[156:159], v[238:241], 0
	v_mfma_f32_16x16x32_bf16 v[0:3], v[164:167], v[238:241], 0
	v_mfma_f32_16x16x32_bf16 v[52:55], v[160:163], v[200:203], v[52:55]
	v_mfma_f32_16x16x32_bf16 v[48:51], v[184:187], v[200:203], v[48:51]
	v_mfma_f32_16x16x32_bf16 v[36:39], v[160:163], v[208:211], v[36:39]
	v_mfma_f32_16x16x32_bf16 v[32:35], v[184:187], v[208:211], v[32:35]
	v_mfma_f32_16x16x32_bf16 v[20:23], v[160:163], v[234:237], v[20:23]
	v_mfma_f32_16x16x32_bf16 v[16:19], v[184:187], v[234:237], v[16:19]
	v_mfma_f32_16x16x32_bf16 v[4:7], v[160:163], v[242:245], v[4:7]
	v_mfma_f32_16x16x32_bf16 v[0:3], v[184:187], v[242:245], v[0:3]
	s_barrier
	s_add_i32 s24, 0, 0x18000
	s_add_i32 s25, 0, 0x1c000
	v_add_u32_e32 v152, s24, v193
	v_add_u32_e32 v170, s25, v193
	ds_read_b128 v[128:131], v152
	ds_read_b128 v[132:135], v152 offset:1024
	ds_read_b128 v[136:139], v152 offset:2048
	ds_read_b128 v[152:155], v152 offset:3072
	ds_read_b128 v[156:159], v170
	ds_read_b128 v[160:163], v170 offset:1024
	ds_read_b128 v[164:167], v170 offset:2048
	ds_read_b128 v[184:187], v170 offset:3072
	s_add_u32 s18, s36, 0x160000
	s_addc_u32 s19, s37, 0
	s_mov_b32 m0, s46
	v_lshl_add_u64 v[170:171], s[18:19], 0, v[146:147]
	ds_read_b128 v[188:191], v198 offset:32768
	ds_read_b128 v[200:203], v198 offset:33792
	ds_read_b128 v[204:207], v198 offset:34816
	ds_read_b128 v[208:211], v198 offset:35840
	ds_read_b128 v[230:233], v198 offset:36864
	ds_read_b128 v[234:237], v198 offset:37888
	ds_read_b128 v[238:241], v198 offset:38912
	ds_read_b128 v[242:245], v198 offset:39936
	global_load_lds_dwordx4 v[170:171], off
	v_lshl_add_u64 v[170:171], s[18:19], 0, v[142:143]
	s_mov_b32 m0, s47
	s_nop 0
	global_load_lds_dwordx4 v[170:171], off
	s_waitcnt vmcnt(8)
	s_waitcnt lgkmcnt(0)
	s_barrier
	v_mfma_f32_16x16x32_bf16 v[124:127], v[128:131], v[188:191], v[124:127]
	v_mfma_f32_16x16x32_bf16 v[120:123], v[136:139], v[188:191], v[120:123]
	v_mfma_f32_16x16x32_bf16 v[116:119], v[128:131], v[204:207], v[116:119]
	v_mfma_f32_16x16x32_bf16 v[108:111], v[136:139], v[204:207], v[108:111]
	v_mfma_f32_16x16x32_bf16 v[92:95], v[128:131], v[230:233], v[92:95]
	v_mfma_f32_16x16x32_bf16 v[88:91], v[136:139], v[230:233], v[88:91]
	v_mfma_f32_16x16x32_bf16 v[80:83], v[128:131], v[238:241], v[80:83]
	v_mfma_f32_16x16x32_bf16 v[72:75], v[136:139], v[238:241], v[72:75]
	v_mfma_f32_16x16x32_bf16 v[124:127], v[132:135], v[200:203], v[124:127]
	v_mfma_f32_16x16x32_bf16 v[120:123], v[152:155], v[200:203], v[120:123]
	v_mfma_f32_16x16x32_bf16 v[116:119], v[132:135], v[208:211], v[116:119]
	v_mfma_f32_16x16x32_bf16 v[108:111], v[152:155], v[208:211], v[108:111]
	v_mfma_f32_16x16x32_bf16 v[92:95], v[132:135], v[234:237], v[92:95]
	v_mfma_f32_16x16x32_bf16 v[88:91], v[152:155], v[234:237], v[88:91]
	v_mfma_f32_16x16x32_bf16 v[80:83], v[132:135], v[242:245], v[80:83]
	v_mfma_f32_16x16x32_bf16 v[72:75], v[152:155], v[242:245], v[72:75]
	v_mfma_f32_16x16x32_bf16 v[112:115], v[156:159], v[188:191], v[112:115]
	v_mfma_f32_16x16x32_bf16 v[104:107], v[164:167], v[188:191], v[104:107]
	v_mfma_f32_16x16x32_bf16 v[100:103], v[156:159], v[204:207], v[100:103]
	v_mfma_f32_16x16x32_bf16 v[96:99], v[164:167], v[204:207], v[96:99]
	v_mfma_f32_16x16x32_bf16 v[84:87], v[156:159], v[230:233], v[84:87]
	v_mfma_f32_16x16x32_bf16 v[76:79], v[164:167], v[230:233], v[76:79]
	v_mfma_f32_16x16x32_bf16 v[68:71], v[156:159], v[238:241], v[68:71]
	v_mfma_f32_16x16x32_bf16 v[64:67], v[164:167], v[238:241], v[64:67]
	v_mfma_f32_16x16x32_bf16 v[112:115], v[160:163], v[200:203], v[112:115]
	v_mfma_f32_16x16x32_bf16 v[104:107], v[184:187], v[200:203], v[104:107]
	v_mfma_f32_16x16x32_bf16 v[100:103], v[160:163], v[208:211], v[100:103]
	v_mfma_f32_16x16x32_bf16 v[96:99], v[184:187], v[208:211], v[96:99]
	v_mfma_f32_16x16x32_bf16 v[84:87], v[160:163], v[234:237], v[84:87]
	v_mfma_f32_16x16x32_bf16 v[76:79], v[184:187], v[234:237], v[76:79]
	v_mfma_f32_16x16x32_bf16 v[68:71], v[160:163], v[242:245], v[68:71]
	v_mfma_f32_16x16x32_bf16 v[64:67], v[184:187], v[242:245], v[64:67]
	s_barrier
; #define PG8_STAGE(bufoff, gbase, voff) do { _Pragma("unroll") for (int _i = 0; _i < 2; ++_i) \
;         __builtin_amdgcn_global_load_lds((const unsigned*)((const char*)(gbase) + (voff)[_i]), (LAS unsigned*)(lds + (bufoff) + ldsw + _i * 8192), 16, 0, 0); } while (0)
; #define PG8_LDA(dst, b, h) do { _Pragma("unroll") for (int m = 0; m < 4; ++m) _Pragma("unroll") for (int k = 0; k < 2; ++k) dst[m][k] = *(const LAS bf16x8*)(lds + PG8_SA(b, h) + aoff + m * 2048 + k * 1024); } while (0)
; #define PG8_WAIT_V(n) asm volatile("s_waitcnt vmcnt(" #n ")" ::: "memory")
; #define PG8_WAIT_L(n) asm volatile("s_waitcnt lgkmcnt(" #n ")" ::: "memory")
; template <class Epi>
; __device__ __forceinline__ void gemm_phase(LAS unsigned char* lds, const Gemm g, const StaticOrder& S, const Epi& E, const int tid) {
;     ...
;     for (;;) {
;         const bool has_next = S.next(ui + 1, nxt);
;         const char* nA = has_next ? PG8_APTR(nxt) : cA; const char* nB = has_next ? PG8_BPTR(nxt) : cB;
;         for (int t = 0; t < nt; t += 2) {
;             const bool last = (t == nt - 2);
;             const char* a1 = cA + (size_t)(t + 1) * kstep;
;             const char* a2 = last ? nA : cA + (size_t)(t + 2) * kstep; const char* b2 = last ? nB : cB + (size_t)(t + 2) * kstep;
;             const char* a3 = a2 + kstep; const char* b3 = b2 + kstep;
;             PG8_LDB(B0, 0, 0); PG8_LDB(B1, 0, 1); PG8_SCHED; PG8_LDA(At, 0, 0); PG8_STAGE(PG8_SA(1, 1), a1 + hsA, voffA);
;             PG8_WAIT_V(8); PG8_WAIT_L(0); PG8_BAR; PG8_MMA(0, 0, At, B0); PG8_MMA(0, 1, At, B1); PG8_BAR; PG8_SCHED;
;             PG8_LDA(At, 0, 1); PG8_STAGE(PG8_SB(0, 0), b2, voffB); PG8_STAGE(PG8_SB(0, 1), b2 + hsB, voffB); PG8_STAGE(PG8_SA(0, 0), a2, voffA);
;             PG8_WAIT_V(8); PG8_WAIT_L(0); PG8_BAR; PG8_MMA(1, 0, At, B0); PG8_MMA(1, 1, At, B1); PG8_BAR; PG8_SCHED;
;             PG8_LDB(B0, 1, 0); PG8_LDB(B1, 1, 1); PG8_SCHED; PG8_LDA(At, 1, 0); PG8_STAGE(PG8_SA(0, 1), a2 + hsA, voffA);
;             PG8_WAIT_V(8); PG8_WAIT_L(0); PG8_BAR; PG8_MMA(0, 0, At, B0); PG8_MMA(0, 1, At, B1); PG8_BAR; PG8_SCHED;
;             PG8_LDA(At, 1, 1); PG8_STAGE(PG8_SB(1, 0), b3, voffB); PG8_STAGE(PG8_SB(1, 1), b3 + hsB, voffB); PG8_STAGE(PG8_SA(1, 0), a3, voffA);
;             PG8_WAIT_V(8); PG8_WAIT_L(0); PG8_BAR; PG8_MMA(1, 0, At, B0); PG8_MMA(1, 1, At, B1); PG8_BAR; PG8_SCHED;
	s_add_i32 s18, s24, s39
	v_lshl_add_u64 v[170:171], v[212:213], 0, s[28:29]
	s_mov_b32 m0, s18
	ds_read_b128 v[188:191], v198 offset:49152
	ds_read_b128 v[200:203], v198 offset:50176
	ds_read_b128 v[204:207], v198 offset:51200
	ds_read_b128 v[208:211], v198 offset:52224
	ds_read_b128 v[230:233], v198 offset:53248
	ds_read_b128 v[234:237], v198 offset:54272
	ds_read_b128 v[238:241], v198 offset:55296
	ds_read_b128 v[242:245], v198 offset:56320
	global_load_lds_dwordx4 v[170:171], off
	s_add_i32 m0, s18, 0x2000
	s_add_u32 s18, s34, 0x160080
	v_lshl_add_u64 v[170:171], v[246:247], 0, s[28:29]
	s_addc_u32 s19, s35, 0
	s_add_i32 s24, s25, s39
	global_load_lds_dwordx4 v[170:171], off
	v_lshl_add_u64 v[170:171], s[18:19], 0, v[144:145]
	s_mov_b32 m0, s24
	s_nop 0
	global_load_lds_dwordx4 v[170:171], off
	v_lshl_add_u64 v[170:171], s[18:19], 0, v[140:141]
	s_add_i32 m0, s24, 0x2000
	s_nop 0
	global_load_lds_dwordx4 v[170:171], off
	v_lshl_add_u64 v[170:171], v[248:249], 0, s[28:29]
	s_mov_b32 m0, s56
	s_nop 0
	global_load_lds_dwordx4 v[170:171], off
	v_lshl_add_u64 v[170:171], v[250:251], 0, s[28:29]
	s_mov_b32 m0, s57
	s_nop 0
	global_load_lds_dwordx4 v[170:171], off
	s_waitcnt vmcnt(8)
	s_waitcnt lgkmcnt(0)
	s_barrier
	v_mfma_f32_16x16x32_bf16 v[60:63], v[128:131], v[188:191], v[60:63]
	v_mfma_f32_16x16x32_bf16 v[56:59], v[136:139], v[188:191], v[56:59]
	v_mfma_f32_16x16x32_bf16 v[44:47], v[128:131], v[204:207], v[44:47]
	v_mfma_f32_16x16x32_bf16 v[40:43], v[136:139], v[204:207], v[40:43]
	v_mfma_f32_16x16x32_bf16 v[28:31], v[128:131], v[230:233], v[28:31]
	v_mfma_f32_16x16x32_bf16 v[24:27], v[136:139], v[230:233], v[24:27]
	v_mfma_f32_16x16x32_bf16 v[12:15], v[128:131], v[238:241], v[12:15]
	v_mfma_f32_16x16x32_bf16 v[8:11], v[136:139], v[238:241], v[8:11]
	v_mfma_f32_16x16x32_bf16 v[60:63], v[132:135], v[200:203], v[60:63]
	v_mfma_f32_16x16x32_bf16 v[56:59], v[152:155], v[200:203], v[56:59]
	v_mfma_f32_16x16x32_bf16 v[44:47], v[132:135], v[208:211], v[44:47]
	v_mfma_f32_16x16x32_bf16 v[40:43], v[152:155], v[208:211], v[40:43]
	v_mfma_f32_16x16x32_bf16 v[28:31], v[132:135], v[234:237], v[28:31]
	v_mfma_f32_16x16x32_bf16 v[24:27], v[152:155], v[234:237], v[24:27]
	v_mfma_f32_16x16x32_bf16 v[12:15], v[132:135], v[242:245], v[12:15]
	v_mfma_f32_16x16x32_bf16 v[8:11], v[152:155], v[242:245], v[8:11]
	v_mfma_f32_16x16x32_bf16 v[52:55], v[156:159], v[188:191], v[52:55]
	v_mfma_f32_16x16x32_bf16 v[48:51], v[164:167], v[188:191], v[48:51]
	v_mfma_f32_16x16x32_bf16 v[36:39], v[156:159], v[204:207], v[36:39]
	v_mfma_f32_16x16x32_bf16 v[32:35], v[164:167], v[204:207], v[32:35]
	v_mfma_f32_16x16x32_bf16 v[20:23], v[156:159], v[230:233], v[20:23]
	v_mfma_f32_16x16x32_bf16 v[16:19], v[164:167], v[230:233], v[16:19]
	v_mfma_f32_16x16x32_bf16 v[4:7], v[156:159], v[238:241], v[4:7]
	v_mfma_f32_16x16x32_bf16 v[0:3], v[164:167], v[238:241], v[0:3]
	v_mfma_f32_16x16x32_bf16 v[52:55], v[160:163], v[200:203], v[52:55]
	v_mfma_f32_16x16x32_bf16 v[48:51], v[184:187], v[200:203], v[48:51]
	v_mfma_f32_16x16x32_bf16 v[36:39], v[160:163], v[208:211], v[36:39]
	v_mfma_f32_16x16x32_bf16 v[32:35], v[184:187], v[208:211], v[32:35]
	v_mfma_f32_16x16x32_bf16 v[20:23], v[160:163], v[234:237], v[20:23]
	v_mfma_f32_16x16x32_bf16 v[16:19], v[184:187], v[234:237], v[16:19]
	v_mfma_f32_16x16x32_bf16 v[4:7], v[160:163], v[242:245], v[4:7]
	v_mfma_f32_16x16x32_bf16 v[0:3], v[184:187], v[242:245], v[0:3]
	s_barrier
	s_add_i32 s69, s69, 2
	s_add_u32 s42, s42, 0x100
	s_addc_u32 s43, s43, 0
	s_cmpk_gt_u32 s69, 0x55
	s_mov_b64 s[18:19], s[0:1]

; #define PG8_STAGE(bufoff, gbase, voff) do { _Pragma("unroll") for (int _i = 0; _i < 2; ++_i) \
;         __builtin_amdgcn_global_load_lds((const unsigned*)((const char*)(gbase) + (voff)[_i]), (LAS unsigned*)(lds + (bufoff) + ldsw + _i * 8192), 16, 0, 0); } while (0)
; #define PG8_LDA(dst, b, h) do { _Pragma("unroll") for (int m = 0; m < 4; ++m) _Pragma("unroll") for (int k = 0; k < 2; ++k) dst[m][k] = *(const LAS bf16x8*)(lds + PG8_SA(b, h) + aoff + m * 2048 + k * 1024); } while (0)
; #define PG8_LDB(dst, b, h) do { _Pragma("unroll") for (int n = 0; n < 2; ++n) _Pragma("unroll") for (int k = 0; k < 2; ++k) dst[n][k] = *(const LAS bf16x8*)(lds + PG8_SB(b, h) + boff + n * 2048 + k * 1024); } while (0)
; #define PG8_WAIT_V(n) asm volatile("s_waitcnt vmcnt(" #n ")" ::: "memory")
; #define PG8_WAIT_L(n) asm volatile("s_waitcnt lgkmcnt(" #n ")" ::: "memory")
; template <class Epi>
; __device__ __forceinline__ void gemm_phase(LAS unsigned char* lds, const Gemm g, const StaticOrder& S, const Epi& E, const int tid) {
;     ...
;         for (int t = 0; t < nt; t += 2) {
;             const bool last = (t == nt - 2);
;             const char* a1 = cA + (size_t)(t + 1) * kstep;
;             const char* a2 = last ? nA : cA + (size_t)(t + 2) * kstep; const char* b2 = last ? nB : cB + (size_t)(t + 2) * kstep;
;             const char* a3 = a2 + kstep; const char* b3 = b2 + kstep;
;             PG8_LDB(B0, 0, 0); PG8_LDB(B1, 0, 1); PG8_SCHED; PG8_LDA(At, 0, 0); PG8_STAGE(PG8_SA(1, 1), a1 + hsA, voffA);
;             PG8_WAIT_V(8); PG8_WAIT_L(0); PG8_BAR; PG8_MMA(0, 0, At, B0); PG8_MMA(0, 1, At, B1); PG8_BAR; PG8_SCHED;
;             PG8_LDA(At, 0, 1); PG8_STAGE(PG8_SB(0, 0), b2, voffB); PG8_STAGE(PG8_SB(0, 1), b2 + hsB, voffB); PG8_STAGE(PG8_SA(0, 0), a2, voffA);
;             PG8_WAIT_V(8); PG8_WAIT_L(0); PG8_BAR; PG8_MMA(1, 0, At, B0); PG8_MMA(1, 1, At, B1); PG8_BAR; PG8_SCHED;
;             PG8_LDB(B0, 1, 0); PG8_LDB(B1, 1, 1); PG8_SCHED; PG8_LDA(At, 1, 0); PG8_STAGE(PG8_SA(0, 1), a2 + hsA, voffA);
;             PG8_WAIT_V(8); PG8_WAIT_L(0); PG8_BAR; PG8_MMA(0, 0, At, B0); PG8_MMA(0, 1, At, B1); PG8_BAR; PG8_SCHED;
;             PG8_LDA(At, 1, 1); PG8_STAGE(PG8_SB(1, 0), b3, voffB); PG8_STAGE(PG8_SB(1, 1), b3 + hsB, voffB); PG8_STAGE(PG8_SA(1, 0), a3, voffA);
;             PG8_WAIT_V(8); PG8_WAIT_L(0); PG8_BAR; PG8_MMA(1, 0, At, B0); PG8_MMA(1, 1, At, B1); PG8_BAR; PG8_SCHED;
.LBB0_353:
	s_ashr_i32 s49, s48, 31
	s_lshl_b64 s[10:11], s[48:49], 20
	s_add_u32 s52, s38, s10
	s_addc_u32 s53, s39, s11
	s_and_b64 s[10:11], s[40:41], exec
	s_cselect_b32 s10, s53, s1
	s_cselect_b32 s11, s52, s0
	s_ashr_i32 s47, s46, 31
	s_lshl_b64 s[12:13], s[46:47], 20
	v_readlane_b32 s16, v255, 32
	s_add_u32 s12, s16, s12
	v_readlane_b32 s16, v255, 33
	s_addc_u32 s13, s16, s13
	s_and_b64 s[36:37], s[40:41], exec
	s_cselect_b32 s47, s13, s43
	s_cselect_b32 s49, s12, s42
	s_add_u32 s36, s0, 0x80080
	s_addc_u32 s37, s1, 0
	s_add_u32 s69, s42, 0x100
	s_addc_u32 vcc_lo, s43, 0
	s_mov_b32 vcc_hi, -2
	s_cmp_lg_u64 s[34:35], 0
	s_cbranch_scc0 .Lgprio_c
	s_setprio 1
.Lgprio_c:
	s_add_u32 s0, s36, 0xfff80080
	s_addc_u32 s1, s37, -1
	s_add_i32 s24, 0, 0x10000
	s_cmp_eq_u32 vcc_hi, 28
	s_cselect_b32 s43, s10, s1
	s_cselect_b32 s42, s11, s0
	v_add_u32_e32 v143, s24, v163
	s_cselect_b32 s1, s47, vcc_lo
	s_cselect_b32 s0, s49, s69
	s_add_i32 s55, 0, 0x14000
	ds_read_b128 v[144:147], v143
	ds_read_b128 v[148:151], v143 offset:1024
	ds_read_b128 v[152:155], v143 offset:2048
	ds_read_b128 v[156:159], v143 offset:3072
	v_add_u32_e32 v143, s55, v163
	ds_read_b128 v[184:187], v143
	ds_read_b128 v[188:191], v143 offset:1024
	ds_read_b128 v[192:195], v143 offset:2048
	ds_read_b128 v[196:199], v143 offset:3072
	v_lshl_add_u64 v[160:161], s[36:37], 0, v[138:139]
	s_add_i32 m0, s58, 0xc000
	ds_read_b128 v[200:203], v165
	ds_read_b128 v[204:207], v165 offset:1024
	ds_read_b128 v[208:211], v165 offset:2048
	ds_read_b128 v[232:235], v165 offset:3072
	ds_read_b128 v[236:239], v165 offset:4096
	ds_read_b128 v[240:243], v165 offset:5120
	ds_read_b128 v[244:247], v165 offset:6144
	ds_read_b128 v[248:251], v165 offset:7168
	global_load_lds_dwordx4 v[160:161], off
	v_lshl_add_u64 v[160:161], s[36:37], 0, v[140:141]
	s_add_i32 m0, s58, 0xe000
	s_nop 0
	global_load_lds_dwordx4 v[160:161], off
	s_waitcnt vmcnt(8)
	s_waitcnt lgkmcnt(0)
	s_barrier
	v_mfma_f32_16x16x32_bf16 v[124:127], v[144:147], v[200:203], 0
	v_mfma_f32_16x16x32_bf16 v[120:123], v[152:155], v[200:203], 0
	v_mfma_f32_16x16x32_bf16 v[108:111], v[144:147], v[208:211], 0
	v_mfma_f32_16x16x32_bf16 v[104:107], v[152:155], v[208:211], 0
	v_mfma_f32_16x16x32_bf16 v[92:95], v[144:147], v[236:239], 0
	v_mfma_f32_16x16x32_bf16 v[88:91], v[152:155], v[236:239], 0
	v_mfma_f32_16x16x32_bf16 v[76:79], v[144:147], v[244:247], 0
	v_mfma_f32_16x16x32_bf16 v[72:75], v[152:155], v[244:247], 0
	v_mfma_f32_16x16x32_bf16 v[124:127], v[148:151], v[204:207], v[124:127]
	v_mfma_f32_16x16x32_bf16 v[120:123], v[156:159], v[204:207], v[120:123]
	v_mfma_f32_16x16x32_bf16 v[108:111], v[148:151], v[232:235], v[108:111]
	v_mfma_f32_16x16x32_bf16 v[104:107], v[156:159], v[232:235], v[104:107]
	v_mfma_f32_16x16x32_bf16 v[92:95], v[148:151], v[240:243], v[92:95]
	v_mfma_f32_16x16x32_bf16 v[88:91], v[156:159], v[240:243], v[88:91]
	v_mfma_f32_16x16x32_bf16 v[76:79], v[148:151], v[248:251], v[76:79]
	v_mfma_f32_16x16x32_bf16 v[72:75], v[156:159], v[248:251], v[72:75]
	v_mfma_f32_16x16x32_bf16 v[116:119], v[184:187], v[200:203], 0
	v_mfma_f32_16x16x32_bf16 v[112:115], v[192:195], v[200:203], 0
	v_mfma_f32_16x16x32_bf16 v[100:103], v[184:187], v[208:211], 0
	v_mfma_f32_16x16x32_bf16 v[96:99], v[192:195], v[208:211], 0
	v_mfma_f32_16x16x32_bf16 v[84:87], v[184:187], v[236:239], 0
	v_mfma_f32_16x16x32_bf16 v[80:83], v[192:195], v[236:239], 0
	v_mfma_f32_16x16x32_bf16 v[68:71], v[184:187], v[244:247], 0
	v_mfma_f32_16x16x32_bf16 v[64:67], v[192:195], v[244:247], 0
	v_mfma_f32_16x16x32_bf16 v[116:119], v[188:191], v[204:207], v[116:119]
	v_mfma_f32_16x16x32_bf16 v[112:115], v[196:199], v[204:207], v[112:115]
	v_mfma_f32_16x16x32_bf16 v[100:103], v[188:191], v[232:235], v[100:103]
	v_mfma_f32_16x16x32_bf16 v[96:99], v[196:199], v[232:235], v[96:99]
	v_mfma_f32_16x16x32_bf16 v[84:87], v[188:191], v[240:243], v[84:87]
	v_mfma_f32_16x16x32_bf16 v[80:83], v[196:199], v[240:243], v[80:83]
	v_mfma_f32_16x16x32_bf16 v[68:71], v[188:191], v[248:251], v[68:71]
	v_mfma_f32_16x16x32_bf16 v[64:67], v[196:199], v[248:251], v[64:67]
	s_barrier
	s_add_i32 s24, s24, s57
	v_lshl_add_u64 v[160:161], s[0:1], 0, v[132:133]
	s_mov_b32 m0, s24
	ds_read_b128 v[200:203], v165 offset:16384
	ds_read_b128 v[204:207], v165 offset:17408
	ds_read_b128 v[208:211], v165 offset:18432
	ds_read_b128 v[232:235], v165 offset:19456
	ds_read_b128 v[236:239], v165 offset:20480
	ds_read_b128 v[240:243], v165 offset:21504
	ds_read_b128 v[244:247], v165 offset:22528
	ds_read_b128 v[248:251], v165 offset:23552
	global_load_lds_dwordx4 v[160:161], off
	s_add_i32 m0, s24, 0x2000
	s_add_u32 s24, s0, 0x80000
	v_lshl_add_u64 v[166:167], s[0:1], 0, v[128:129]
	s_addc_u32 s25, s1, 0
	s_add_i32 s55, s55, s57
	global_load_lds_dwordx4 v[166:167], off
	v_lshl_add_u64 v[170:171], s[24:25], 0, v[132:133]
	s_mov_b32 m0, s55
	v_lshl_add_u64 v[212:213], s[42:43], 0, v[130:131]
	global_load_lds_dwordx4 v[170:171], off
	v_lshl_add_u64 v[170:171], s[24:25], 0, v[128:129]
	s_add_i32 m0, s55, 0x2000
	s_nop 0
	global_load_lds_dwordx4 v[170:171], off
	v_lshl_add_u64 v[170:171], s[42:43], 0, v[134:135]
	s_mov_b32 m0, s58
	s_nop 0
	global_load_lds_dwordx4 v[170:171], off
	s_mov_b32 m0, s59
	s_nop 0
	global_load_lds_dwordx4 v[212:213], off
	s_waitcnt vmcnt(8)
	s_waitcnt lgkmcnt(0)
	s_barrier
; #define PG8_STAGE(bufoff, gbase, voff) do { _Pragma("unroll") for (int _i = 0; _i < 2; ++_i) \
;         __builtin_amdgcn_global_load_lds((const unsigned*)((const char*)(gbase) + (voff)[_i]), (LAS unsigned*)(lds + (bufoff) + ldsw + _i * 8192), 16, 0, 0); } while (0)
; #define PG8_LDA(dst, b, h) do { _Pragma("unroll") for (int m = 0; m < 4; ++m) _Pragma("unroll") for (int k = 0; k < 2; ++k) dst[m][k] = *(const LAS bf16x8*)(lds + PG8_SA(b, h) + aoff + m * 2048 + k * 1024); } while (0)
; #define PG8_LDB(dst, b, h) do { _Pragma("unroll") for (int n = 0; n < 2; ++n) _Pragma("unroll") for (int k = 0; k < 2; ++k) dst[n][k] = *(const LAS bf16x8*)(lds + PG8_SB(b, h) + boff + n * 2048 + k * 1024); } while (0)
; #define PG8_WAIT_V(n) asm volatile("s_waitcnt vmcnt(" #n ")" ::: "memory")
; #define PG8_WAIT_L(n) asm volatile("s_waitcnt lgkmcnt(" #n ")" ::: "memory")
; template <class Epi>
; __device__ __forceinline__ void gemm_phase(LAS unsigned char* lds, const Gemm g, const StaticOrder& S, const Epi& E, const int tid) {
;     ...
;         for (int t = 0; t < nt; t += 2) {
;             const bool last = (t == nt - 2);
;             const char* a1 = cA + (size_t)(t + 1) * kstep;
;             const char* a2 = last ? nA : cA + (size_t)(t + 2) * kstep; const char* b2 = last ? nB : cB + (size_t)(t + 2) * kstep;
;             const char* a3 = a2 + kstep; const char* b3 = b2 + kstep;
;             PG8_LDB(B0, 0, 0); PG8_LDB(B1, 0, 1); PG8_SCHED; PG8_LDA(At, 0, 0); PG8_STAGE(PG8_SA(1, 1), a1 + hsA, voffA);
;             PG8_WAIT_V(8); PG8_WAIT_L(0); PG8_BAR; PG8_MMA(0, 0, At, B0); PG8_MMA(0, 1, At, B1); PG8_BAR; PG8_SCHED;
;             PG8_LDA(At, 0, 1); PG8_STAGE(PG8_SB(0, 0), b2, voffB); PG8_STAGE(PG8_SB(0, 1), b2 + hsB, voffB); PG8_STAGE(PG8_SA(0, 0), a2, voffA);
;             PG8_WAIT_V(8); PG8_WAIT_L(0); PG8_BAR; PG8_MMA(1, 0, At, B0); PG8_MMA(1, 1, At, B1); PG8_BAR; PG8_SCHED;
;             PG8_LDB(B0, 1, 0); PG8_LDB(B1, 1, 1); PG8_SCHED; PG8_LDA(At, 1, 0); PG8_STAGE(PG8_SA(0, 1), a2 + hsA, voffA);
;             PG8_WAIT_V(8); PG8_WAIT_L(0); PG8_BAR; PG8_MMA(0, 0, At, B0); PG8_MMA(0, 1, At, B1); PG8_BAR; PG8_SCHED;
;             PG8_LDA(At, 1, 1); PG8_STAGE(PG8_SB(1, 0), b3, voffB); PG8_STAGE(PG8_SB(1, 1), b3 + hsB, voffB); PG8_STAGE(PG8_SA(1, 0), a3, voffA);
;             PG8_WAIT_V(8); PG8_WAIT_L(0); PG8_BAR; PG8_MMA(1, 0, At, B0); PG8_MMA(1, 1, At, B1); PG8_BAR; PG8_SCHED;
	v_mfma_f32_16x16x32_bf16 v[60:63], v[144:147], v[200:203], 0
	v_mfma_f32_16x16x32_bf16 v[56:59], v[152:155], v[200:203], 0
	v_mfma_f32_16x16x32_bf16 v[44:47], v[144:147], v[208:211], 0
	v_mfma_f32_16x16x32_bf16 v[40:43], v[152:155], v[208:211], 0
	v_mfma_f32_16x16x32_bf16 v[28:31], v[144:147], v[236:239], 0
	v_mfma_f32_16x16x32_bf16 v[24:27], v[152:155], v[236:239], 0
	v_mfma_f32_16x16x32_bf16 v[12:15], v[144:147], v[244:247], 0
	v_mfma_f32_16x16x32_bf16 v[8:11], v[152:155], v[244:247], 0
	v_mfma_f32_16x16x32_bf16 v[60:63], v[148:151], v[204:207], v[60:63]
	v_mfma_f32_16x16x32_bf16 v[56:59], v[156:159], v[204:207], v[56:59]
	v_mfma_f32_16x16x32_bf16 v[44:47], v[148:151], v[232:235], v[44:47]
	v_mfma_f32_16x16x32_bf16 v[40:43], v[156:159], v[232:235], v[40:43]
	v_mfma_f32_16x16x32_bf16 v[28:31], v[148:151], v[240:243], v[28:31]
	v_mfma_f32_16x16x32_bf16 v[24:27], v[156:159], v[240:243], v[24:27]
	v_mfma_f32_16x16x32_bf16 v[12:15], v[148:151], v[248:251], v[12:15]
	v_mfma_f32_16x16x32_bf16 v[8:11], v[156:159], v[248:251], v[8:11]
	v_mfma_f32_16x16x32_bf16 v[52:55], v[184:187], v[200:203], 0
	v_mfma_f32_16x16x32_bf16 v[48:51], v[192:195], v[200:203], 0
	v_mfma_f32_16x16x32_bf16 v[36:39], v[184:187], v[208:211], 0
	v_mfma_f32_16x16x32_bf16 v[32:35], v[192:195], v[208:211], 0
	v_mfma_f32_16x16x32_bf16 v[20:23], v[184:187], v[236:239], 0
	v_mfma_f32_16x16x32_bf16 v[16:19], v[192:195], v[236:239], 0
	v_mfma_f32_16x16x32_bf16 v[4:7], v[184:187], v[244:247], 0
	v_mfma_f32_16x16x32_bf16 v[0:3], v[192:195], v[244:247], 0
	v_mfma_f32_16x16x32_bf16 v[52:55], v[188:191], v[204:207], v[52:55]
	v_mfma_f32_16x16x32_bf16 v[48:51], v[196:199], v[204:207], v[48:51]
	v_mfma_f32_16x16x32_bf16 v[36:39], v[188:191], v[232:235], v[36:39]
	v_mfma_f32_16x16x32_bf16 v[32:35], v[196:199], v[232:235], v[32:35]
	v_mfma_f32_16x16x32_bf16 v[20:23], v[188:191], v[240:243], v[20:23]
	v_mfma_f32_16x16x32_bf16 v[16:19], v[196:199], v[240:243], v[16:19]
	v_mfma_f32_16x16x32_bf16 v[4:7], v[188:191], v[248:251], v[4:7]
	v_mfma_f32_16x16x32_bf16 v[0:3], v[196:199], v[248:251], v[0:3]
	s_barrier
	s_add_i32 s55, 0, 0x18000
	v_add_u32_e32 v143, s55, v163
	s_add_i32 s67, 0, 0x1c000
	ds_read_b128 v[144:147], v143
	ds_read_b128 v[148:151], v143 offset:1024
	ds_read_b128 v[152:155], v143 offset:2048
	ds_read_b128 v[156:159], v143 offset:3072
	v_add_u32_e32 v143, s67, v163
	ds_read_b128 v[184:187], v143
	ds_read_b128 v[188:191], v143 offset:1024
	ds_read_b128 v[192:195], v143 offset:2048
	ds_read_b128 v[196:199], v143 offset:3072
	s_add_u32 s24, s42, 0x80000
	s_addc_u32 s25, s43, 0
	s_mov_b32 m0, s27
	v_lshl_add_u64 v[172:173], s[24:25], 0, v[134:135]
	ds_read_b128 v[200:203], v165 offset:32768
	ds_read_b128 v[204:207], v165 offset:33792
	ds_read_b128 v[208:211], v165 offset:34816
	ds_read_b128 v[232:235], v165 offset:35840
	ds_read_b128 v[236:239], v165 offset:36864
	ds_read_b128 v[240:243], v165 offset:37888
	ds_read_b128 v[244:247], v165 offset:38912
	ds_read_b128 v[248:251], v165 offset:39936
	global_load_lds_dwordx4 v[172:173], off
	v_lshl_add_u64 v[172:173], s[24:25], 0, v[130:131]
	s_mov_b32 m0, s96
	s_nop 0
	global_load_lds_dwordx4 v[172:173], off
	s_waitcnt vmcnt(8)
	s_waitcnt lgkmcnt(0)
	s_barrier
	v_mfma_f32_16x16x32_bf16 v[124:127], v[144:147], v[200:203], v[124:127]
	v_mfma_f32_16x16x32_bf16 v[120:123], v[152:155], v[200:203], v[120:123]
	v_mfma_f32_16x16x32_bf16 v[108:111], v[144:147], v[208:211], v[108:111]
	v_mfma_f32_16x16x32_bf16 v[104:107], v[152:155], v[208:211], v[104:107]
	v_mfma_f32_16x16x32_bf16 v[92:95], v[144:147], v[236:239], v[92:95]
	v_mfma_f32_16x16x32_bf16 v[88:91], v[152:155], v[236:239], v[88:91]
	v_mfma_f32_16x16x32_bf16 v[76:79], v[144:147], v[244:247], v[76:79]
	v_mfma_f32_16x16x32_bf16 v[72:75], v[152:155], v[244:247], v[72:75]
	v_mfma_f32_16x16x32_bf16 v[124:127], v[148:151], v[204:207], v[124:127]
	v_mfma_f32_16x16x32_bf16 v[120:123], v[156:159], v[204:207], v[120:123]
	v_mfma_f32_16x16x32_bf16 v[108:111], v[148:151], v[232:235], v[108:111]
	v_mfma_f32_16x16x32_bf16 v[104:107], v[156:159], v[232:235], v[104:107]
	v_mfma_f32_16x16x32_bf16 v[92:95], v[148:151], v[240:243], v[92:95]
	v_mfma_f32_16x16x32_bf16 v[88:91], v[156:159], v[240:243], v[88:91]
	v_mfma_f32_16x16x32_bf16 v[76:79], v[148:151], v[248:251], v[76:79]
	v_mfma_f32_16x16x32_bf16 v[72:75], v[156:159], v[248:251], v[72:75]
	v_mfma_f32_16x16x32_bf16 v[116:119], v[184:187], v[200:203], v[116:119]
	v_mfma_f32_16x16x32_bf16 v[112:115], v[192:195], v[200:203], v[112:115]
	v_mfma_f32_16x16x32_bf16 v[100:103], v[184:187], v[208:211], v[100:103]
	v_mfma_f32_16x16x32_bf16 v[96:99], v[192:195], v[208:211], v[96:99]
	v_mfma_f32_16x16x32_bf16 v[84:87], v[184:187], v[236:239], v[84:87]
	v_mfma_f32_16x16x32_bf16 v[80:83], v[192:195], v[236:239], v[80:83]
	v_mfma_f32_16x16x32_bf16 v[68:71], v[184:187], v[244:247], v[68:71]
	v_mfma_f32_16x16x32_bf16 v[64:67], v[192:195], v[244:247], v[64:67]
	v_mfma_f32_16x16x32_bf16 v[116:119], v[188:191], v[204:207], v[116:119]
	v_mfma_f32_16x16x32_bf16 v[112:115], v[196:199], v[204:207], v[112:115]
	v_mfma_f32_16x16x32_bf16 v[100:103], v[188:191], v[232:235], v[100:103]
	v_mfma_f32_16x16x32_bf16 v[96:99], v[196:199], v[232:235], v[96:99]
	v_mfma_f32_16x16x32_bf16 v[84:87], v[188:191], v[240:243], v[84:87]
	v_mfma_f32_16x16x32_bf16 v[80:83], v[196:199], v[240:243], v[80:83]
	v_mfma_f32_16x16x32_bf16 v[68:71], v[188:191], v[248:251], v[68:71]
	v_mfma_f32_16x16x32_bf16 v[64:67], v[196:199], v[248:251], v[64:67]
	s_barrier
; #define PG8_STAGE(bufoff, gbase, voff) do { _Pragma("unroll") for (int _i = 0; _i < 2; ++_i) \
;         __builtin_amdgcn_global_load_lds((const unsigned*)((const char*)(gbase) + (voff)[_i]), (LAS unsigned*)(lds + (bufoff) + ldsw + _i * 8192), 16, 0, 0); } while (0)
; #define PG8_LDA(dst, b, h) do { _Pragma("unroll") for (int m = 0; m < 4; ++m) _Pragma("unroll") for (int k = 0; k < 2; ++k) dst[m][k] = *(const LAS bf16x8*)(lds + PG8_SA(b, h) + aoff + m * 2048 + k * 1024); } while (0)
; #define PG8_WAIT_V(n) asm volatile("s_waitcnt vmcnt(" #n ")" ::: "memory")
; #define PG8_WAIT_L(n) asm volatile("s_waitcnt lgkmcnt(" #n ")" ::: "memory")
; template <class Epi>
; __device__ __forceinline__ void gemm_phase(LAS unsigned char* lds, const Gemm g, const StaticOrder& S, const Epi& E, const int tid) {
;     ...
;     for (;;) {
;         const bool has_next = S.next(ui + 1, nxt);
;         const char* nA = has_next ? PG8_APTR(nxt) : cA; const char* nB = has_next ? PG8_BPTR(nxt) : cB;
;         for (int t = 0; t < nt; t += 2) {
;             const bool last = (t == nt - 2);
;             const char* a1 = cA + (size_t)(t + 1) * kstep;
;             const char* a2 = last ? nA : cA + (size_t)(t + 2) * kstep; const char* b2 = last ? nB : cB + (size_t)(t + 2) * kstep;
;             const char* a3 = a2 + kstep; const char* b3 = b2 + kstep;
;             PG8_LDB(B0, 0, 0); PG8_LDB(B1, 0, 1); PG8_SCHED; PG8_LDA(At, 0, 0); PG8_STAGE(PG8_SA(1, 1), a1 + hsA, voffA);
;             PG8_WAIT_V(8); PG8_WAIT_L(0); PG8_BAR; PG8_MMA(0, 0, At, B0); PG8_MMA(0, 1, At, B1); PG8_BAR; PG8_SCHED;
;             PG8_LDA(At, 0, 1); PG8_STAGE(PG8_SB(0, 0), b2, voffB); PG8_STAGE(PG8_SB(0, 1), b2 + hsB, voffB); PG8_STAGE(PG8_SA(0, 0), a2, voffA);
;             PG8_WAIT_V(8); PG8_WAIT_L(0); PG8_BAR; PG8_MMA(1, 0, At, B0); PG8_MMA(1, 1, At, B1); PG8_BAR; PG8_SCHED;
;             PG8_LDB(B0, 1, 0); PG8_LDB(B1, 1, 1); PG8_SCHED; PG8_LDA(At, 1, 0); PG8_STAGE(PG8_SA(0, 1), a2 + hsA, voffA);
;             PG8_WAIT_V(8); PG8_WAIT_L(0); PG8_BAR; PG8_MMA(0, 0, At, B0); PG8_MMA(0, 1, At, B1); PG8_BAR; PG8_SCHED;
;             PG8_LDA(At, 1, 1); PG8_STAGE(PG8_SB(1, 0), b3, voffB); PG8_STAGE(PG8_SB(1, 1), b3 + hsB, voffB); PG8_STAGE(PG8_SA(1, 0), a3, voffA);
;             PG8_WAIT_V(8); PG8_WAIT_L(0); PG8_BAR; PG8_MMA(1, 0, At, B0); PG8_MMA(1, 1, At, B1); PG8_BAR; PG8_SCHED;
	s_add_i32 s24, s55, s57
	v_lshl_add_u64 v[160:161], v[160:161], 0, s[28:29]
	s_mov_b32 m0, s24
	ds_read_b128 v[200:203], v165 offset:49152
	ds_read_b128 v[204:207], v165 offset:50176
	ds_read_b128 v[208:211], v165 offset:51200
	ds_read_b128 v[232:235], v165 offset:52224
	ds_read_b128 v[236:239], v165 offset:53248
	ds_read_b128 v[240:243], v165 offset:54272
	ds_read_b128 v[244:247], v165 offset:55296
	ds_read_b128 v[248:251], v165 offset:56320
	global_load_lds_dwordx4 v[160:161], off
	s_add_i32 m0, s24, 0x2000
	s_add_u32 s0, s0, 0x80080
	v_lshl_add_u64 v[160:161], v[166:167], 0, s[28:29]
	s_addc_u32 s1, s1, 0
	s_add_i32 s24, s67, s57
	global_load_lds_dwordx4 v[160:161], off
	v_lshl_add_u64 v[160:161], s[0:1], 0, v[132:133]
	s_mov_b32 m0, s24
	s_nop 0
	global_load_lds_dwordx4 v[160:161], off
	v_lshl_add_u64 v[160:161], s[0:1], 0, v[128:129]
	s_add_i32 m0, s24, 0x2000
	s_nop 0
	global_load_lds_dwordx4 v[160:161], off
	v_lshl_add_u64 v[160:161], v[170:171], 0, s[28:29]
	s_mov_b32 m0, s6
	s_nop 0
	global_load_lds_dwordx4 v[160:161], off
	v_lshl_add_u64 v[160:161], v[212:213], 0, s[28:29]
	s_mov_b32 m0, s7
	s_nop 0
	global_load_lds_dwordx4 v[160:161], off
	s_waitcnt vmcnt(8)
	s_waitcnt lgkmcnt(0)
	s_barrier
	v_mfma_f32_16x16x32_bf16 v[60:63], v[144:147], v[200:203], v[60:63]
	v_mfma_f32_16x16x32_bf16 v[56:59], v[152:155], v[200:203], v[56:59]
	v_mfma_f32_16x16x32_bf16 v[44:47], v[144:147], v[208:211], v[44:47]
	v_mfma_f32_16x16x32_bf16 v[40:43], v[152:155], v[208:211], v[40:43]
	v_mfma_f32_16x16x32_bf16 v[28:31], v[144:147], v[236:239], v[28:31]
	v_mfma_f32_16x16x32_bf16 v[24:27], v[152:155], v[236:239], v[24:27]
	v_mfma_f32_16x16x32_bf16 v[12:15], v[144:147], v[244:247], v[12:15]
	v_mfma_f32_16x16x32_bf16 v[8:11], v[152:155], v[244:247], v[8:11]
	v_mfma_f32_16x16x32_bf16 v[60:63], v[148:151], v[204:207], v[60:63]
	v_mfma_f32_16x16x32_bf16 v[56:59], v[156:159], v[204:207], v[56:59]
	v_mfma_f32_16x16x32_bf16 v[44:47], v[148:151], v[232:235], v[44:47]
	v_mfma_f32_16x16x32_bf16 v[40:43], v[156:159], v[232:235], v[40:43]
	v_mfma_f32_16x16x32_bf16 v[28:31], v[148:151], v[240:243], v[28:31]
	v_mfma_f32_16x16x32_bf16 v[24:27], v[156:159], v[240:243], v[24:27]
	v_mfma_f32_16x16x32_bf16 v[12:15], v[148:151], v[248:251], v[12:15]
	v_mfma_f32_16x16x32_bf16 v[8:11], v[156:159], v[248:251], v[8:11]
	v_mfma_f32_16x16x32_bf16 v[52:55], v[184:187], v[200:203], v[52:55]
	v_mfma_f32_16x16x32_bf16 v[48:51], v[192:195], v[200:203], v[48:51]
	v_mfma_f32_16x16x32_bf16 v[36:39], v[184:187], v[208:211], v[36:39]
	v_mfma_f32_16x16x32_bf16 v[32:35], v[192:195], v[208:211], v[32:35]
	v_mfma_f32_16x16x32_bf16 v[20:23], v[184:187], v[236:239], v[20:23]
	v_mfma_f32_16x16x32_bf16 v[16:19], v[192:195], v[236:239], v[16:19]
	v_mfma_f32_16x16x32_bf16 v[4:7], v[184:187], v[244:247], v[4:7]
	v_mfma_f32_16x16x32_bf16 v[0:3], v[192:195], v[244:247], v[0:3]
	v_mfma_f32_16x16x32_bf16 v[52:55], v[188:191], v[204:207], v[52:55]
	v_mfma_f32_16x16x32_bf16 v[48:51], v[196:199], v[204:207], v[48:51]
	v_mfma_f32_16x16x32_bf16 v[36:39], v[188:191], v[232:235], v[36:39]
	v_mfma_f32_16x16x32_bf16 v[32:35], v[196:199], v[232:235], v[32:35]
	v_mfma_f32_16x16x32_bf16 v[20:23], v[188:191], v[240:243], v[20:23]
	v_mfma_f32_16x16x32_bf16 v[16:19], v[196:199], v[240:243], v[16:19]
	v_mfma_f32_16x16x32_bf16 v[4:7], v[188:191], v[248:251], v[4:7]
	v_mfma_f32_16x16x32_bf16 v[0:3], v[196:199], v[248:251], v[0:3]
	s_barrier
	s_add_i32 vcc_hi, vcc_hi, 2
	s_add_u32 s36, s36, 0x100
	s_addc_u32 s37, s37, 0
	s_add_u32 s69, s69, 0x100
	s_addc_u32 vcc_lo, vcc_lo, 0
	s_cmp_gt_u32 vcc_hi, 29

; #define PG8_STAGE(bufoff, gbase, voff) do { _Pragma("unroll") for (int _i = 0; _i < 2; ++_i) \
;         __builtin_amdgcn_global_load_lds((const unsigned*)((const char*)(gbase) + (voff)[_i]), (LAS unsigned*)(lds + (bufoff) + ldsw + _i * 8192), 16, 0, 0); } while (0)
; #define PG8_LDA(dst, b, h) do { _Pragma("unroll") for (int m = 0; m < 4; ++m) _Pragma("unroll") for (int k = 0; k < 2; ++k) dst[m][k] = *(const LAS bf16x8*)(lds + PG8_SA(b, h) + aoff + m * 2048 + k * 1024); } while (0)
; #define PG8_LDB(dst, b, h) do { _Pragma("unroll") for (int n = 0; n < 2; ++n) _Pragma("unroll") for (int k = 0; k < 2; ++k) dst[n][k] = *(const LAS bf16x8*)(lds + PG8_SB(b, h) + boff + n * 2048 + k * 1024); } while (0)
; #define PG8_WAIT_V(n) asm volatile("s_waitcnt vmcnt(" #n ")" ::: "memory")
; #define PG8_WAIT_L(n) asm volatile("s_waitcnt lgkmcnt(" #n ")" ::: "memory")
; template <class Epi>
; __device__ __forceinline__ void gemm_phase(LAS unsigned char* lds, const Gemm g, const StaticOrder& S, const Epi& E, const int tid) {
;     ...
;         for (int t = 0; t < nt; t += 2) {
;             const bool last = (t == nt - 2);
;             const char* a1 = cA + (size_t)(t + 1) * kstep;
;             const char* a2 = last ? nA : cA + (size_t)(t + 2) * kstep; const char* b2 = last ? nB : cB + (size_t)(t + 2) * kstep;
;             const char* a3 = a2 + kstep; const char* b3 = b2 + kstep;
;             PG8_LDB(B0, 0, 0); PG8_LDB(B1, 0, 1); PG8_SCHED; PG8_LDA(At, 0, 0); PG8_STAGE(PG8_SA(1, 1), a1 + hsA, voffA);
;             PG8_WAIT_V(8); PG8_WAIT_L(0); PG8_BAR; PG8_MMA(0, 0, At, B0); PG8_MMA(0, 1, At, B1); PG8_BAR; PG8_SCHED;
;             PG8_LDA(At, 0, 1); PG8_STAGE(PG8_SB(0, 0), b2, voffB); PG8_STAGE(PG8_SB(0, 1), b2 + hsB, voffB); PG8_STAGE(PG8_SA(0, 0), a2, voffA);
;             PG8_WAIT_V(8); PG8_WAIT_L(0); PG8_BAR; PG8_MMA(1, 0, At, B0); PG8_MMA(1, 1, At, B1); PG8_BAR; PG8_SCHED;
;             PG8_LDB(B0, 1, 0); PG8_LDB(B1, 1, 1); PG8_SCHED; PG8_LDA(At, 1, 0); PG8_STAGE(PG8_SA(0, 1), a2 + hsA, voffA);
;             PG8_WAIT_V(8); PG8_WAIT_L(0); PG8_BAR; PG8_MMA(0, 0, At, B0); PG8_MMA(0, 1, At, B1); PG8_BAR; PG8_SCHED;
;             PG8_LDA(At, 1, 1); PG8_STAGE(PG8_SB(1, 0), b3, voffB); PG8_STAGE(PG8_SB(1, 1), b3 + hsB, voffB); PG8_STAGE(PG8_SA(1, 0), a3, voffA);
;             PG8_WAIT_V(8); PG8_WAIT_L(0); PG8_BAR; PG8_MMA(1, 0, At, B0); PG8_MMA(1, 1, At, B1); PG8_BAR; PG8_SCHED;
.LBB0_1003:
	s_ashr_i32 s13, s12, 31
	s_lshl_b64 s[14:15], s[12:13], 20
	s_add_u32 s14, s58, s14
	s_addc_u32 s15, s59, s15
	s_and_b64 s[16:17], s[38:39], exec
	s_cselect_b32 s13, s15, s19
	s_cselect_b32 s49, s14, s18
	s_ashr_i32 s11, s10, 31
	s_lshl_b64 s[16:17], s[10:11], 20
	s_add_u32 s16, s36, s16
	s_addc_u32 s17, s37, s17
	s_and_b64 s[24:25], s[38:39], exec
	s_cselect_b32 s11, s17, s1
	s_cselect_b32 s52, s16, s0
	s_add_u32 s18, s18, 0x80080
	s_addc_u32 s19, s19, 0
	s_add_u32 s53, s0, 0x100
	s_addc_u32 s56, s1, 0
	s_mov_b32 s57, -2
	s_cmp_lg_u64 s[8:9], 0
	s_cbranch_scc0 .Lgprio_f
	s_setprio 1
.Lgprio_f:
	s_add_u32 s0, s18, 0xfff80080
	s_addc_u32 s1, s19, -1
	s_add_i32 s2, 0, 0x10000
	s_cmp_eq_u32 s57, 28
	s_cselect_b32 s35, s13, s1
	s_cselect_b32 s34, s49, s0
	s_cselect_b32 s1, s11, s56
	s_cselect_b32 s0, s52, s53
	s_add_i32 s55, 0, 0x14000
	v_add_u32_e32 v154, s2, v143
	v_add_u32_e32 v166, s55, v143
	ds_read_b128 v[138:141], v154
	ds_read_b128 v[146:149], v154 offset:1024
	ds_read_b128 v[150:153], v154 offset:2048
	ds_read_b128 v[154:157], v154 offset:3072
	ds_read_b128 v[158:161], v166
	ds_read_b128 v[162:165], v166 offset:1024
	ds_read_b128 v[184:187], v166 offset:2048
	ds_read_b128 v[188:191], v166 offset:3072
	v_lshl_add_u64 v[166:167], s[18:19], 0, v[134:135]
	s_add_i32 m0, s40, 0xc000
	ds_read_b128 v[192:195], v145
	ds_read_b128 v[196:199], v145 offset:1024
	ds_read_b128 v[200:203], v145 offset:2048
	ds_read_b128 v[204:207], v145 offset:3072
	ds_read_b128 v[208:211], v145 offset:4096
	ds_read_b128 v[230:233], v145 offset:5120
	ds_read_b128 v[234:237], v145 offset:6144
	ds_read_b128 v[238:241], v145 offset:7168
	global_load_lds_dwordx4 v[166:167], off
	v_lshl_add_u64 v[166:167], s[18:19], 0, v[136:137]
	s_add_i32 m0, s40, 0xe000
	s_nop 0
	global_load_lds_dwordx4 v[166:167], off
	s_waitcnt vmcnt(8)
	s_waitcnt lgkmcnt(0)
	s_barrier
	v_mfma_f32_16x16x32_bf16 v[124:127], v[138:141], v[192:195], 0
	v_mfma_f32_16x16x32_bf16 v[116:119], v[150:153], v[192:195], 0
	v_mfma_f32_16x16x32_bf16 v[108:111], v[138:141], v[200:203], 0
	v_mfma_f32_16x16x32_bf16 v[100:103], v[150:153], v[200:203], 0
	v_mfma_f32_16x16x32_bf16 v[92:95], v[138:141], v[208:211], 0
	v_mfma_f32_16x16x32_bf16 v[84:87], v[150:153], v[208:211], 0
	v_mfma_f32_16x16x32_bf16 v[76:79], v[138:141], v[234:237], 0
	v_mfma_f32_16x16x32_bf16 v[68:71], v[150:153], v[234:237], 0
	v_mfma_f32_16x16x32_bf16 v[124:127], v[146:149], v[196:199], v[124:127]
	v_mfma_f32_16x16x32_bf16 v[116:119], v[154:157], v[196:199], v[116:119]
	v_mfma_f32_16x16x32_bf16 v[108:111], v[146:149], v[204:207], v[108:111]
	v_mfma_f32_16x16x32_bf16 v[100:103], v[154:157], v[204:207], v[100:103]
	v_mfma_f32_16x16x32_bf16 v[92:95], v[146:149], v[230:233], v[92:95]
	v_mfma_f32_16x16x32_bf16 v[84:87], v[154:157], v[230:233], v[84:87]
	v_mfma_f32_16x16x32_bf16 v[76:79], v[146:149], v[238:241], v[76:79]
	v_mfma_f32_16x16x32_bf16 v[68:71], v[154:157], v[238:241], v[68:71]
	v_mfma_f32_16x16x32_bf16 v[120:123], v[158:161], v[192:195], 0
	v_mfma_f32_16x16x32_bf16 v[112:115], v[184:187], v[192:195], 0
	v_mfma_f32_16x16x32_bf16 v[104:107], v[158:161], v[200:203], 0
	v_mfma_f32_16x16x32_bf16 v[96:99], v[184:187], v[200:203], 0
	v_mfma_f32_16x16x32_bf16 v[88:91], v[158:161], v[208:211], 0
	v_mfma_f32_16x16x32_bf16 v[80:83], v[184:187], v[208:211], 0
	v_mfma_f32_16x16x32_bf16 v[72:75], v[158:161], v[234:237], 0
	v_mfma_f32_16x16x32_bf16 v[64:67], v[184:187], v[234:237], 0
	v_mfma_f32_16x16x32_bf16 v[120:123], v[162:165], v[196:199], v[120:123]
	v_mfma_f32_16x16x32_bf16 v[112:115], v[188:191], v[196:199], v[112:115]
	v_mfma_f32_16x16x32_bf16 v[104:107], v[162:165], v[204:207], v[104:107]
	v_mfma_f32_16x16x32_bf16 v[96:99], v[188:191], v[204:207], v[96:99]
	v_mfma_f32_16x16x32_bf16 v[88:91], v[162:165], v[230:233], v[88:91]
	v_mfma_f32_16x16x32_bf16 v[80:83], v[188:191], v[230:233], v[80:83]
	v_mfma_f32_16x16x32_bf16 v[72:75], v[162:165], v[238:241], v[72:75]
	v_mfma_f32_16x16x32_bf16 v[64:67], v[188:191], v[238:241], v[64:67]
	s_barrier
	s_add_i32 s2, s2, s27
	v_lshl_add_u64 v[166:167], s[0:1], 0, v[168:169]
	s_mov_b32 m0, s2
	ds_read_b128 v[192:195], v145 offset:16384
	ds_read_b128 v[196:199], v145 offset:17408
	ds_read_b128 v[200:203], v145 offset:18432
	ds_read_b128 v[204:207], v145 offset:19456
	ds_read_b128 v[208:211], v145 offset:20480
	ds_read_b128 v[230:233], v145 offset:21504
	ds_read_b128 v[234:237], v145 offset:22528
	ds_read_b128 v[238:241], v145 offset:23552
	global_load_lds_dwordx4 v[166:167], off
	s_add_i32 m0, s2, 0x2000
	s_add_u32 s24, s0, 0x80000
	v_lshl_add_u64 v[170:171], s[0:1], 0, v[132:133]
	s_addc_u32 s25, s1, 0
	s_add_i32 s2, s55, s27
	global_load_lds_dwordx4 v[170:171], off
	v_lshl_add_u64 v[172:173], s[24:25], 0, v[168:169]
	s_mov_b32 m0, s2
	v_lshl_add_u64 v[212:213], s[34:35], 0, v[130:131]
	global_load_lds_dwordx4 v[172:173], off
	v_lshl_add_u64 v[172:173], s[24:25], 0, v[132:133]
	s_add_i32 m0, s2, 0x2000
	s_nop 0
	global_load_lds_dwordx4 v[172:173], off
	v_lshl_add_u64 v[172:173], s[34:35], 0, v[128:129]
	s_mov_b32 m0, s40
	s_nop 0
	global_load_lds_dwordx4 v[172:173], off
	s_mov_b32 m0, s41
	s_nop 0
	global_load_lds_dwordx4 v[212:213], off
	s_waitcnt vmcnt(8)
	s_waitcnt lgkmcnt(0)
	s_barrier
; #define PG8_STAGE(bufoff, gbase, voff) do { _Pragma("unroll") for (int _i = 0; _i < 2; ++_i) \
;         __builtin_amdgcn_global_load_lds((const unsigned*)((const char*)(gbase) + (voff)[_i]), (LAS unsigned*)(lds + (bufoff) + ldsw + _i * 8192), 16, 0, 0); } while (0)
; #define PG8_LDA(dst, b, h) do { _Pragma("unroll") for (int m = 0; m < 4; ++m) _Pragma("unroll") for (int k = 0; k < 2; ++k) dst[m][k] = *(const LAS bf16x8*)(lds + PG8_SA(b, h) + aoff + m * 2048 + k * 1024); } while (0)
; #define PG8_LDB(dst, b, h) do { _Pragma("unroll") for (int n = 0; n < 2; ++n) _Pragma("unroll") for (int k = 0; k < 2; ++k) dst[n][k] = *(const LAS bf16x8*)(lds + PG8_SB(b, h) + boff + n * 2048 + k * 1024); } while (0)
; #define PG8_WAIT_V(n) asm volatile("s_waitcnt vmcnt(" #n ")" ::: "memory")
; #define PG8_WAIT_L(n) asm volatile("s_waitcnt lgkmcnt(" #n ")" ::: "memory")
; template <class Epi>
; __device__ __forceinline__ void gemm_phase(LAS unsigned char* lds, const Gemm g, const StaticOrder& S, const Epi& E, const int tid) {
;     ...
;         for (int t = 0; t < nt; t += 2) {
;             const bool last = (t == nt - 2);
;             const char* a1 = cA + (size_t)(t + 1) * kstep;
;             const char* a2 = last ? nA : cA + (size_t)(t + 2) * kstep; const char* b2 = last ? nB : cB + (size_t)(t + 2) * kstep;
;             const char* a3 = a2 + kstep; const char* b3 = b2 + kstep;
;             PG8_LDB(B0, 0, 0); PG8_LDB(B1, 0, 1); PG8_SCHED; PG8_LDA(At, 0, 0); PG8_STAGE(PG8_SA(1, 1), a1 + hsA, voffA);
;             PG8_WAIT_V(8); PG8_WAIT_L(0); PG8_BAR; PG8_MMA(0, 0, At, B0); PG8_MMA(0, 1, At, B1); PG8_BAR; PG8_SCHED;
;             PG8_LDA(At, 0, 1); PG8_STAGE(PG8_SB(0, 0), b2, voffB); PG8_STAGE(PG8_SB(0, 1), b2 + hsB, voffB); PG8_STAGE(PG8_SA(0, 0), a2, voffA);
;             PG8_WAIT_V(8); PG8_WAIT_L(0); PG8_BAR; PG8_MMA(1, 0, At, B0); PG8_MMA(1, 1, At, B1); PG8_BAR; PG8_SCHED;
;             PG8_LDB(B0, 1, 0); PG8_LDB(B1, 1, 1); PG8_SCHED; PG8_LDA(At, 1, 0); PG8_STAGE(PG8_SA(0, 1), a2 + hsA, voffA);
;             PG8_WAIT_V(8); PG8_WAIT_L(0); PG8_BAR; PG8_MMA(0, 0, At, B0); PG8_MMA(0, 1, At, B1); PG8_BAR; PG8_SCHED;
;             PG8_LDA(At, 1, 1); PG8_STAGE(PG8_SB(1, 0), b3, voffB); PG8_STAGE(PG8_SB(1, 1), b3 + hsB, voffB); PG8_STAGE(PG8_SA(1, 0), a3, voffA);
;             PG8_WAIT_V(8); PG8_WAIT_L(0); PG8_BAR; PG8_MMA(1, 0, At, B0); PG8_MMA(1, 1, At, B1); PG8_BAR; PG8_SCHED;
	v_mfma_f32_16x16x32_bf16 v[60:63], v[138:141], v[192:195], 0
	v_mfma_f32_16x16x32_bf16 v[52:55], v[150:153], v[192:195], 0
	v_mfma_f32_16x16x32_bf16 v[44:47], v[138:141], v[200:203], 0
	v_mfma_f32_16x16x32_bf16 v[36:39], v[150:153], v[200:203], 0
	v_mfma_f32_16x16x32_bf16 v[28:31], v[138:141], v[208:211], 0
	v_mfma_f32_16x16x32_bf16 v[20:23], v[150:153], v[208:211], 0
	v_mfma_f32_16x16x32_bf16 v[12:15], v[138:141], v[234:237], 0
	v_mfma_f32_16x16x32_bf16 v[4:7], v[150:153], v[234:237], 0
	v_mfma_f32_16x16x32_bf16 v[60:63], v[146:149], v[196:199], v[60:63]
	v_mfma_f32_16x16x32_bf16 v[52:55], v[154:157], v[196:199], v[52:55]
	v_mfma_f32_16x16x32_bf16 v[44:47], v[146:149], v[204:207], v[44:47]
	v_mfma_f32_16x16x32_bf16 v[36:39], v[154:157], v[204:207], v[36:39]
	v_mfma_f32_16x16x32_bf16 v[28:31], v[146:149], v[230:233], v[28:31]
	v_mfma_f32_16x16x32_bf16 v[20:23], v[154:157], v[230:233], v[20:23]
	v_mfma_f32_16x16x32_bf16 v[12:15], v[146:149], v[238:241], v[12:15]
	v_mfma_f32_16x16x32_bf16 v[4:7], v[154:157], v[238:241], v[4:7]
	v_mfma_f32_16x16x32_bf16 v[56:59], v[158:161], v[192:195], 0
	v_mfma_f32_16x16x32_bf16 v[48:51], v[184:187], v[192:195], 0
	v_mfma_f32_16x16x32_bf16 v[40:43], v[158:161], v[200:203], 0
	v_mfma_f32_16x16x32_bf16 v[32:35], v[184:187], v[200:203], 0
	v_mfma_f32_16x16x32_bf16 v[24:27], v[158:161], v[208:211], 0
	v_mfma_f32_16x16x32_bf16 v[16:19], v[184:187], v[208:211], 0
	v_mfma_f32_16x16x32_bf16 v[8:11], v[158:161], v[234:237], 0
	v_mfma_f32_16x16x32_bf16 v[0:3], v[184:187], v[234:237], 0
	v_mfma_f32_16x16x32_bf16 v[56:59], v[162:165], v[196:199], v[56:59]
	v_mfma_f32_16x16x32_bf16 v[48:51], v[188:191], v[196:199], v[48:51]
	v_mfma_f32_16x16x32_bf16 v[40:43], v[162:165], v[204:207], v[40:43]
	v_mfma_f32_16x16x32_bf16 v[32:35], v[188:191], v[204:207], v[32:35]
	v_mfma_f32_16x16x32_bf16 v[24:27], v[162:165], v[230:233], v[24:27]
	v_mfma_f32_16x16x32_bf16 v[16:19], v[188:191], v[230:233], v[16:19]
	v_mfma_f32_16x16x32_bf16 v[8:11], v[162:165], v[238:241], v[8:11]
	v_mfma_f32_16x16x32_bf16 v[0:3], v[188:191], v[238:241], v[0:3]
	s_barrier
	s_add_i32 s2, 0, 0x18000
	s_add_i32 s55, 0, 0x1c000
	v_add_u32_e32 v154, s2, v143
	v_add_u32_e32 v188, s55, v143
	ds_read_b128 v[138:141], v154
	ds_read_b128 v[146:149], v154 offset:1024
	ds_read_b128 v[150:153], v154 offset:2048
	ds_read_b128 v[154:157], v154 offset:3072
	ds_read_b128 v[158:161], v188
	ds_read_b128 v[162:165], v188 offset:1024
	ds_read_b128 v[184:187], v188 offset:2048
	ds_read_b128 v[188:191], v188 offset:3072
	s_add_u32 s24, s34, 0x80000
	s_addc_u32 s25, s35, 0
	s_mov_b32 m0, s42
	v_lshl_add_u64 v[242:243], s[24:25], 0, v[128:129]
	ds_read_b128 v[192:195], v145 offset:32768
	ds_read_b128 v[196:199], v145 offset:33792
	ds_read_b128 v[200:203], v145 offset:34816
	ds_read_b128 v[204:207], v145 offset:35840
	ds_read_b128 v[208:211], v145 offset:36864
	ds_read_b128 v[230:233], v145 offset:37888
	ds_read_b128 v[234:237], v145 offset:38912
	ds_read_b128 v[238:241], v145 offset:39936
	global_load_lds_dwordx4 v[242:243], off
	v_lshl_add_u64 v[242:243], s[24:25], 0, v[130:131]
	s_mov_b32 m0, s43
	s_nop 0
	global_load_lds_dwordx4 v[242:243], off
	s_waitcnt vmcnt(8)
	s_waitcnt lgkmcnt(0)
	s_barrier
	v_mfma_f32_16x16x32_bf16 v[124:127], v[138:141], v[192:195], v[124:127]
	v_mfma_f32_16x16x32_bf16 v[116:119], v[150:153], v[192:195], v[116:119]
	v_mfma_f32_16x16x32_bf16 v[108:111], v[138:141], v[200:203], v[108:111]
	v_mfma_f32_16x16x32_bf16 v[100:103], v[150:153], v[200:203], v[100:103]
	v_mfma_f32_16x16x32_bf16 v[92:95], v[138:141], v[208:211], v[92:95]
	v_mfma_f32_16x16x32_bf16 v[84:87], v[150:153], v[208:211], v[84:87]
	v_mfma_f32_16x16x32_bf16 v[76:79], v[138:141], v[234:237], v[76:79]
	v_mfma_f32_16x16x32_bf16 v[68:71], v[150:153], v[234:237], v[68:71]
	v_mfma_f32_16x16x32_bf16 v[124:127], v[146:149], v[196:199], v[124:127]
	v_mfma_f32_16x16x32_bf16 v[116:119], v[154:157], v[196:199], v[116:119]
	v_mfma_f32_16x16x32_bf16 v[108:111], v[146:149], v[204:207], v[108:111]
	v_mfma_f32_16x16x32_bf16 v[100:103], v[154:157], v[204:207], v[100:103]
	v_mfma_f32_16x16x32_bf16 v[92:95], v[146:149], v[230:233], v[92:95]
	v_mfma_f32_16x16x32_bf16 v[84:87], v[154:157], v[230:233], v[84:87]
	v_mfma_f32_16x16x32_bf16 v[76:79], v[146:149], v[238:241], v[76:79]
	v_mfma_f32_16x16x32_bf16 v[68:71], v[154:157], v[238:241], v[68:71]
	v_mfma_f32_16x16x32_bf16 v[120:123], v[158:161], v[192:195], v[120:123]
	v_mfma_f32_16x16x32_bf16 v[112:115], v[184:187], v[192:195], v[112:115]
	v_mfma_f32_16x16x32_bf16 v[104:107], v[158:161], v[200:203], v[104:107]
	v_mfma_f32_16x16x32_bf16 v[96:99], v[184:187], v[200:203], v[96:99]
	v_mfma_f32_16x16x32_bf16 v[88:91], v[158:161], v[208:211], v[88:91]
	v_mfma_f32_16x16x32_bf16 v[80:83], v[184:187], v[208:211], v[80:83]
	v_mfma_f32_16x16x32_bf16 v[72:75], v[158:161], v[234:237], v[72:75]
	v_mfma_f32_16x16x32_bf16 v[64:67], v[184:187], v[234:237], v[64:67]
	v_mfma_f32_16x16x32_bf16 v[120:123], v[162:165], v[196:199], v[120:123]
	v_mfma_f32_16x16x32_bf16 v[112:115], v[188:191], v[196:199], v[112:115]
	v_mfma_f32_16x16x32_bf16 v[104:107], v[162:165], v[204:207], v[104:107]
	v_mfma_f32_16x16x32_bf16 v[96:99], v[188:191], v[204:207], v[96:99]
	v_mfma_f32_16x16x32_bf16 v[88:91], v[162:165], v[230:233], v[88:91]
	v_mfma_f32_16x16x32_bf16 v[80:83], v[188:191], v[230:233], v[80:83]
	v_mfma_f32_16x16x32_bf16 v[72:75], v[162:165], v[238:241], v[72:75]
	v_mfma_f32_16x16x32_bf16 v[64:67], v[188:191], v[238:241], v[64:67]
	s_barrier
; #define PG8_STAGE(bufoff, gbase, voff) do { _Pragma("unroll") for (int _i = 0; _i < 2; ++_i) \
;         __builtin_amdgcn_global_load_lds((const unsigned*)((const char*)(gbase) + (voff)[_i]), (LAS unsigned*)(lds + (bufoff) + ldsw + _i * 8192), 16, 0, 0); } while (0)
; #define PG8_LDA(dst, b, h) do { _Pragma("unroll") for (int m = 0; m < 4; ++m) _Pragma("unroll") for (int k = 0; k < 2; ++k) dst[m][k] = *(const LAS bf16x8*)(lds + PG8_SA(b, h) + aoff + m * 2048 + k * 1024); } while (0)
; #define PG8_WAIT_V(n) asm volatile("s_waitcnt vmcnt(" #n ")" ::: "memory")
; #define PG8_WAIT_L(n) asm volatile("s_waitcnt lgkmcnt(" #n ")" ::: "memory")
; template <class Epi>
; __device__ __forceinline__ void gemm_phase(LAS unsigned char* lds, const Gemm g, const StaticOrder& S, const Epi& E, const int tid) {
;     ...
;     for (;;) {
;         const bool has_next = S.next(ui + 1, nxt);
;         const char* nA = has_next ? PG8_APTR(nxt) : cA; const char* nB = has_next ? PG8_BPTR(nxt) : cB;
;         for (int t = 0; t < nt; t += 2) {
;             const bool last = (t == nt - 2);
;             const char* a1 = cA + (size_t)(t + 1) * kstep;
;             const char* a2 = last ? nA : cA + (size_t)(t + 2) * kstep; const char* b2 = last ? nB : cB + (size_t)(t + 2) * kstep;
;             const char* a3 = a2 + kstep; const char* b3 = b2 + kstep;
;             PG8_LDB(B0, 0, 0); PG8_LDB(B1, 0, 1); PG8_SCHED; PG8_LDA(At, 0, 0); PG8_STAGE(PG8_SA(1, 1), a1 + hsA, voffA);
;             PG8_WAIT_V(8); PG8_WAIT_L(0); PG8_BAR; PG8_MMA(0, 0, At, B0); PG8_MMA(0, 1, At, B1); PG8_BAR; PG8_SCHED;
;             PG8_LDA(At, 0, 1); PG8_STAGE(PG8_SB(0, 0), b2, voffB); PG8_STAGE(PG8_SB(0, 1), b2 + hsB, voffB); PG8_STAGE(PG8_SA(0, 0), a2, voffA);
;             PG8_WAIT_V(8); PG8_WAIT_L(0); PG8_BAR; PG8_MMA(1, 0, At, B0); PG8_MMA(1, 1, At, B1); PG8_BAR; PG8_SCHED;
;             PG8_LDB(B0, 1, 0); PG8_LDB(B1, 1, 1); PG8_SCHED; PG8_LDA(At, 1, 0); PG8_STAGE(PG8_SA(0, 1), a2 + hsA, voffA);
;             PG8_WAIT_V(8); PG8_WAIT_L(0); PG8_BAR; PG8_MMA(0, 0, At, B0); PG8_MMA(0, 1, At, B1); PG8_BAR; PG8_SCHED;
;             PG8_LDA(At, 1, 1); PG8_STAGE(PG8_SB(1, 0), b3, voffB); PG8_STAGE(PG8_SB(1, 1), b3 + hsB, voffB); PG8_STAGE(PG8_SA(1, 0), a3, voffA);
;             PG8_WAIT_V(8); PG8_WAIT_L(0); PG8_BAR; PG8_MMA(1, 0, At, B0); PG8_MMA(1, 1, At, B1); PG8_BAR; PG8_SCHED;
	s_add_i32 s2, s2, s27
	v_lshl_add_u64 v[166:167], v[166:167], 0, s[28:29]
	s_mov_b32 m0, s2
	ds_read_b128 v[192:195], v145 offset:49152
	ds_read_b128 v[196:199], v145 offset:50176
	ds_read_b128 v[200:203], v145 offset:51200
	ds_read_b128 v[204:207], v145 offset:52224
	ds_read_b128 v[208:211], v145 offset:53248
	ds_read_b128 v[230:233], v145 offset:54272
	ds_read_b128 v[234:237], v145 offset:55296
	ds_read_b128 v[238:241], v145 offset:56320
	global_load_lds_dwordx4 v[166:167], off
	s_add_i32 m0, s2, 0x2000
	s_add_u32 s0, s0, 0x80080
	v_lshl_add_u64 v[166:167], v[170:171], 0, s[28:29]
	s_addc_u32 s1, s1, 0
	s_add_i32 s2, s55, s27
	global_load_lds_dwordx4 v[166:167], off
	v_lshl_add_u64 v[166:167], s[0:1], 0, v[168:169]
	s_mov_b32 m0, s2
	s_nop 0
	global_load_lds_dwordx4 v[166:167], off
	v_lshl_add_u64 v[166:167], s[0:1], 0, v[132:133]
	s_add_i32 m0, s2, 0x2000
	s_nop 0
	global_load_lds_dwordx4 v[166:167], off
	v_lshl_add_u64 v[166:167], v[172:173], 0, s[28:29]
	s_mov_b32 m0, s44
	s_nop 0
	global_load_lds_dwordx4 v[166:167], off
	v_lshl_add_u64 v[166:167], v[212:213], 0, s[28:29]
	s_mov_b32 m0, s45
	s_nop 0
	global_load_lds_dwordx4 v[166:167], off
	s_waitcnt vmcnt(8)
	s_waitcnt lgkmcnt(0)
	s_barrier
	v_mfma_f32_16x16x32_bf16 v[60:63], v[138:141], v[192:195], v[60:63]
	v_mfma_f32_16x16x32_bf16 v[52:55], v[150:153], v[192:195], v[52:55]
	v_mfma_f32_16x16x32_bf16 v[44:47], v[138:141], v[200:203], v[44:47]
	v_mfma_f32_16x16x32_bf16 v[36:39], v[150:153], v[200:203], v[36:39]
	v_mfma_f32_16x16x32_bf16 v[28:31], v[138:141], v[208:211], v[28:31]
	v_mfma_f32_16x16x32_bf16 v[20:23], v[150:153], v[208:211], v[20:23]
	v_mfma_f32_16x16x32_bf16 v[12:15], v[138:141], v[234:237], v[12:15]
	v_mfma_f32_16x16x32_bf16 v[4:7], v[150:153], v[234:237], v[4:7]
	v_mfma_f32_16x16x32_bf16 v[60:63], v[146:149], v[196:199], v[60:63]
	v_mfma_f32_16x16x32_bf16 v[52:55], v[154:157], v[196:199], v[52:55]
	v_mfma_f32_16x16x32_bf16 v[44:47], v[146:149], v[204:207], v[44:47]
	v_mfma_f32_16x16x32_bf16 v[36:39], v[154:157], v[204:207], v[36:39]
	v_mfma_f32_16x16x32_bf16 v[28:31], v[146:149], v[230:233], v[28:31]
	v_mfma_f32_16x16x32_bf16 v[20:23], v[154:157], v[230:233], v[20:23]
	v_mfma_f32_16x16x32_bf16 v[12:15], v[146:149], v[238:241], v[12:15]
	v_mfma_f32_16x16x32_bf16 v[4:7], v[154:157], v[238:241], v[4:7]
	v_mfma_f32_16x16x32_bf16 v[56:59], v[158:161], v[192:195], v[56:59]
	v_mfma_f32_16x16x32_bf16 v[48:51], v[184:187], v[192:195], v[48:51]
	v_mfma_f32_16x16x32_bf16 v[40:43], v[158:161], v[200:203], v[40:43]
	v_mfma_f32_16x16x32_bf16 v[32:35], v[184:187], v[200:203], v[32:35]
	v_mfma_f32_16x16x32_bf16 v[24:27], v[158:161], v[208:211], v[24:27]
	v_mfma_f32_16x16x32_bf16 v[16:19], v[184:187], v[208:211], v[16:19]
	v_mfma_f32_16x16x32_bf16 v[8:11], v[158:161], v[234:237], v[8:11]
	v_mfma_f32_16x16x32_bf16 v[0:3], v[184:187], v[234:237], v[0:3]
	v_mfma_f32_16x16x32_bf16 v[56:59], v[162:165], v[196:199], v[56:59]
	v_mfma_f32_16x16x32_bf16 v[48:51], v[188:191], v[196:199], v[48:51]
	v_mfma_f32_16x16x32_bf16 v[40:43], v[162:165], v[204:207], v[40:43]
	v_mfma_f32_16x16x32_bf16 v[32:35], v[188:191], v[204:207], v[32:35]
	v_mfma_f32_16x16x32_bf16 v[24:27], v[162:165], v[230:233], v[24:27]
	v_mfma_f32_16x16x32_bf16 v[16:19], v[188:191], v[230:233], v[16:19]
	v_mfma_f32_16x16x32_bf16 v[8:11], v[162:165], v[238:241], v[8:11]
	v_mfma_f32_16x16x32_bf16 v[0:3], v[188:191], v[238:241], v[0:3]
	s_barrier
	s_add_i32 s57, s57, 2
	s_add_u32 s18, s18, 0x100
	s_addc_u32 s19, s19, 0
	s_add_u32 s53, s53, 0x100
	s_addc_u32 s56, s56, 0
	s_cmp_gt_u32 s57, 29

; #define PG8_STAGE(bufoff, gbase, voff) do { _Pragma("unroll") for (int _i = 0; _i < 2; ++_i) \
;         __builtin_amdgcn_global_load_lds((const unsigned*)((const char*)(gbase) + (voff)[_i]), (LAS unsigned*)(lds + (bufoff) + ldsw + _i * 8192), 16, 0, 0); } while (0)
; #define PG8_LDA(dst, b, h) do { _Pragma("unroll") for (int m = 0; m < 4; ++m) _Pragma("unroll") for (int k = 0; k < 2; ++k) dst[m][k] = *(const LAS bf16x8*)(lds + PG8_SA(b, h) + aoff + m * 2048 + k * 1024); } while (0)
; #define PG8_LDB(dst, b, h) do { _Pragma("unroll") for (int n = 0; n < 2; ++n) _Pragma("unroll") for (int k = 0; k < 2; ++k) dst[n][k] = *(const LAS bf16x8*)(lds + PG8_SB(b, h) + boff + n * 2048 + k * 1024); } while (0)
; #define PG8_WAIT_V(n) asm volatile("s_waitcnt vmcnt(" #n ")" ::: "memory")
; #define PG8_WAIT_L(n) asm volatile("s_waitcnt lgkmcnt(" #n ")" ::: "memory")
; template <class Epi>
; __device__ __forceinline__ void gemm_phase(LAS unsigned char* lds, const Gemm g, const StaticOrder& S, const Epi& E, const int tid) {
;     ...
;         for (int t = 0; t < nt; t += 2) {
;             const bool last = (t == nt - 2);
;             const char* a1 = cA + (size_t)(t + 1) * kstep;
;             const char* a2 = last ? nA : cA + (size_t)(t + 2) * kstep; const char* b2 = last ? nB : cB + (size_t)(t + 2) * kstep;
;             const char* a3 = a2 + kstep; const char* b3 = b2 + kstep;
;             PG8_LDB(B0, 0, 0); PG8_LDB(B1, 0, 1); PG8_SCHED; PG8_LDA(At, 0, 0); PG8_STAGE(PG8_SA(1, 1), a1 + hsA, voffA);
;             PG8_WAIT_V(8); PG8_WAIT_L(0); PG8_BAR; PG8_MMA(0, 0, At, B0); PG8_MMA(0, 1, At, B1); PG8_BAR; PG8_SCHED;
;             PG8_LDA(At, 0, 1); PG8_STAGE(PG8_SB(0, 0), b2, voffB); PG8_STAGE(PG8_SB(0, 1), b2 + hsB, voffB); PG8_STAGE(PG8_SA(0, 0), a2, voffA);
;             PG8_WAIT_V(8); PG8_WAIT_L(0); PG8_BAR; PG8_MMA(1, 0, At, B0); PG8_MMA(1, 1, At, B1); PG8_BAR; PG8_SCHED;
;             PG8_LDB(B0, 1, 0); PG8_LDB(B1, 1, 1); PG8_SCHED; PG8_LDA(At, 1, 0); PG8_STAGE(PG8_SA(0, 1), a2 + hsA, voffA);
;             PG8_WAIT_V(8); PG8_WAIT_L(0); PG8_BAR; PG8_MMA(0, 0, At, B0); PG8_MMA(0, 1, At, B1); PG8_BAR; PG8_SCHED;
;             PG8_LDA(At, 1, 1); PG8_STAGE(PG8_SB(1, 0), b3, voffB); PG8_STAGE(PG8_SB(1, 1), b3 + hsB, voffB); PG8_STAGE(PG8_SA(1, 0), a3, voffA);
;             PG8_WAIT_V(8); PG8_WAIT_L(0); PG8_BAR; PG8_MMA(1, 0, At, B0); PG8_MMA(1, 1, At, B1); PG8_BAR; PG8_SCHED;
.LBB0_1075:
	s_add_u32 s38, s0, 0x100
	s_addc_u32 s39, s1, 0
	s_mov_b32 s53, -2
	s_cmp_lg_u64 s[6:7], 0
	s_cbranch_scc0 .Lgprio_g
	s_setprio 1
.Lgprio_g:
	s_add_u32 s0, s12, 0x100
	s_addc_u32 s1, s13, 0
	s_add_i32 s2, 0, 0x10000
	s_cmpk_eq_i32 s53, 0x54
	s_cselect_b32 s17, s9, s1
	s_cselect_b32 s16, s8, s0
	s_cselect_b32 s15, s11, s39
	s_cselect_b32 s14, s10, s38
	s_add_i32 s24, 0, 0x14000
	v_add_u32_e32 v152, s2, v184
	v_add_u32_e32 v170, s24, v184
	ds_read_b128 v[128:131], v152
	ds_read_b128 v[144:147], v152 offset:1024
	ds_read_b128 v[148:151], v152 offset:2048
	ds_read_b128 v[152:155], v152 offset:3072
	ds_read_b128 v[156:159], v170
	ds_read_b128 v[160:163], v170 offset:1024
	ds_read_b128 v[164:167], v170 offset:2048
	ds_read_b128 v[190:193], v170 offset:3072
	v_lshl_add_u64 v[170:171], s[12:13], 0, v[140:141]
	s_add_i32 m0, s34, 0xc000
	ds_read_b128 v[194:197], v189
	ds_read_b128 v[198:201], v189 offset:1024
	ds_read_b128 v[202:205], v189 offset:2048
	ds_read_b128 v[206:209], v189 offset:3072
	ds_read_b128 v[210:213], v189 offset:4096
	ds_read_b128 v[230:233], v189 offset:5120
	ds_read_b128 v[234:237], v189 offset:6144
	ds_read_b128 v[238:241], v189 offset:7168
	global_load_lds_dwordx4 v[170:171], off
	v_lshl_add_u64 v[170:171], s[12:13], 0, v[142:143]
	s_add_i32 m0, s34, 0xe000
	s_nop 0
	global_load_lds_dwordx4 v[170:171], off
	s_waitcnt vmcnt(8)
	s_waitcnt lgkmcnt(0)
	s_barrier
	v_mfma_f32_16x16x32_bf16 v[124:127], v[128:131], v[194:197], 0
	v_mfma_f32_16x16x32_bf16 v[120:123], v[148:151], v[194:197], 0
	v_mfma_f32_16x16x32_bf16 v[108:111], v[128:131], v[202:205], 0
	v_mfma_f32_16x16x32_bf16 v[104:107], v[148:151], v[202:205], 0
	v_mfma_f32_16x16x32_bf16 v[92:95], v[128:131], v[210:213], 0
	v_mfma_f32_16x16x32_bf16 v[88:91], v[148:151], v[210:213], 0
	v_mfma_f32_16x16x32_bf16 v[80:83], v[128:131], v[234:237], 0
	v_mfma_f32_16x16x32_bf16 v[72:75], v[148:151], v[234:237], 0
	v_mfma_f32_16x16x32_bf16 v[124:127], v[144:147], v[198:201], v[124:127]
	v_mfma_f32_16x16x32_bf16 v[120:123], v[152:155], v[198:201], v[120:123]
	v_mfma_f32_16x16x32_bf16 v[108:111], v[144:147], v[206:209], v[108:111]
	v_mfma_f32_16x16x32_bf16 v[104:107], v[152:155], v[206:209], v[104:107]
	v_mfma_f32_16x16x32_bf16 v[92:95], v[144:147], v[230:233], v[92:95]
	v_mfma_f32_16x16x32_bf16 v[88:91], v[152:155], v[230:233], v[88:91]
	v_mfma_f32_16x16x32_bf16 v[80:83], v[144:147], v[238:241], v[80:83]
	v_mfma_f32_16x16x32_bf16 v[72:75], v[152:155], v[238:241], v[72:75]
	v_mfma_f32_16x16x32_bf16 v[116:119], v[156:159], v[194:197], 0
	v_mfma_f32_16x16x32_bf16 v[112:115], v[164:167], v[194:197], 0
	v_mfma_f32_16x16x32_bf16 v[100:103], v[156:159], v[202:205], 0
	v_mfma_f32_16x16x32_bf16 v[96:99], v[164:167], v[202:205], 0
	v_mfma_f32_16x16x32_bf16 v[84:87], v[156:159], v[210:213], 0
	v_mfma_f32_16x16x32_bf16 v[76:79], v[164:167], v[210:213], 0
	v_mfma_f32_16x16x32_bf16 v[68:71], v[156:159], v[234:237], 0
	v_mfma_f32_16x16x32_bf16 v[64:67], v[164:167], v[234:237], 0
	v_mfma_f32_16x16x32_bf16 v[116:119], v[160:163], v[198:201], v[116:119]
	v_mfma_f32_16x16x32_bf16 v[112:115], v[190:193], v[198:201], v[112:115]
	v_mfma_f32_16x16x32_bf16 v[100:103], v[160:163], v[206:209], v[100:103]
	v_mfma_f32_16x16x32_bf16 v[96:99], v[190:193], v[206:209], v[96:99]
	v_mfma_f32_16x16x32_bf16 v[84:87], v[160:163], v[230:233], v[84:87]
	v_mfma_f32_16x16x32_bf16 v[76:79], v[190:193], v[230:233], v[76:79]
	v_mfma_f32_16x16x32_bf16 v[68:71], v[160:163], v[238:241], v[68:71]
	v_mfma_f32_16x16x32_bf16 v[64:67], v[190:193], v[238:241], v[64:67]
	s_barrier
	s_add_i32 s2, s2, s27
	v_lshl_add_u64 v[170:171], s[14:15], 0, v[136:137]
	s_mov_b32 m0, s2
	ds_read_b128 v[194:197], v189 offset:16384
	ds_read_b128 v[198:201], v189 offset:17408
	ds_read_b128 v[202:205], v189 offset:18432
	ds_read_b128 v[206:209], v189 offset:19456
	ds_read_b128 v[210:213], v189 offset:20480
	ds_read_b128 v[230:233], v189 offset:21504
	ds_read_b128 v[234:237], v189 offset:22528
	ds_read_b128 v[238:241], v189 offset:23552
	global_load_lds_dwordx4 v[170:171], off
	s_add_i32 m0, s2, 0x2000
	s_add_u32 s12, s14, 0x160000
	v_lshl_add_u64 v[172:173], s[14:15], 0, v[132:133]
	s_addc_u32 s13, s15, 0
	s_add_i32 s2, s24, s27
	global_load_lds_dwordx4 v[172:173], off
	v_lshl_add_u64 v[242:243], s[12:13], 0, v[136:137]
	s_mov_b32 m0, s2
	v_lshl_add_u64 v[244:245], s[16:17], 0, v[134:135]
	global_load_lds_dwordx4 v[242:243], off
	v_lshl_add_u64 v[242:243], s[12:13], 0, v[132:133]
	s_add_i32 m0, s2, 0x2000
	s_nop 0
	global_load_lds_dwordx4 v[242:243], off
	v_lshl_add_u64 v[242:243], s[16:17], 0, v[138:139]
	s_mov_b32 m0, s34
	s_nop 0
	global_load_lds_dwordx4 v[242:243], off
	s_mov_b32 m0, s35
	s_nop 0
	global_load_lds_dwordx4 v[244:245], off
	s_waitcnt vmcnt(8)
	s_waitcnt lgkmcnt(0)
	s_barrier
; #define PG8_STAGE(bufoff, gbase, voff) do { _Pragma("unroll") for (int _i = 0; _i < 2; ++_i) \
;         __builtin_amdgcn_global_load_lds((const unsigned*)((const char*)(gbase) + (voff)[_i]), (LAS unsigned*)(lds + (bufoff) + ldsw + _i * 8192), 16, 0, 0); } while (0)
; #define PG8_LDA(dst, b, h) do { _Pragma("unroll") for (int m = 0; m < 4; ++m) _Pragma("unroll") for (int k = 0; k < 2; ++k) dst[m][k] = *(const LAS bf16x8*)(lds + PG8_SA(b, h) + aoff + m * 2048 + k * 1024); } while (0)
; #define PG8_LDB(dst, b, h) do { _Pragma("unroll") for (int n = 0; n < 2; ++n) _Pragma("unroll") for (int k = 0; k < 2; ++k) dst[n][k] = *(const LAS bf16x8*)(lds + PG8_SB(b, h) + boff + n * 2048 + k * 1024); } while (0)
; #define PG8_WAIT_V(n) asm volatile("s_waitcnt vmcnt(" #n ")" ::: "memory")
; #define PG8_WAIT_L(n) asm volatile("s_waitcnt lgkmcnt(" #n ")" ::: "memory")
; template <class Epi>
; __device__ __forceinline__ void gemm_phase(LAS unsigned char* lds, const Gemm g, const StaticOrder& S, const Epi& E, const int tid) {
;     ...
;         for (int t = 0; t < nt; t += 2) {
;             const bool last = (t == nt - 2);
;             const char* a1 = cA + (size_t)(t + 1) * kstep;
;             const char* a2 = last ? nA : cA + (size_t)(t + 2) * kstep; const char* b2 = last ? nB : cB + (size_t)(t + 2) * kstep;
;             const char* a3 = a2 + kstep; const char* b3 = b2 + kstep;
;             PG8_LDB(B0, 0, 0); PG8_LDB(B1, 0, 1); PG8_SCHED; PG8_LDA(At, 0, 0); PG8_STAGE(PG8_SA(1, 1), a1 + hsA, voffA);
;             PG8_WAIT_V(8); PG8_WAIT_L(0); PG8_BAR; PG8_MMA(0, 0, At, B0); PG8_MMA(0, 1, At, B1); PG8_BAR; PG8_SCHED;
;             PG8_LDA(At, 0, 1); PG8_STAGE(PG8_SB(0, 0), b2, voffB); PG8_STAGE(PG8_SB(0, 1), b2 + hsB, voffB); PG8_STAGE(PG8_SA(0, 0), a2, voffA);
;             PG8_WAIT_V(8); PG8_WAIT_L(0); PG8_BAR; PG8_MMA(1, 0, At, B0); PG8_MMA(1, 1, At, B1); PG8_BAR; PG8_SCHED;
;             PG8_LDB(B0, 1, 0); PG8_LDB(B1, 1, 1); PG8_SCHED; PG8_LDA(At, 1, 0); PG8_STAGE(PG8_SA(0, 1), a2 + hsA, voffA);
;             PG8_WAIT_V(8); PG8_WAIT_L(0); PG8_BAR; PG8_MMA(0, 0, At, B0); PG8_MMA(0, 1, At, B1); PG8_BAR; PG8_SCHED;
;             PG8_LDA(At, 1, 1); PG8_STAGE(PG8_SB(1, 0), b3, voffB); PG8_STAGE(PG8_SB(1, 1), b3 + hsB, voffB); PG8_STAGE(PG8_SA(1, 0), a3, voffA);
;             PG8_WAIT_V(8); PG8_WAIT_L(0); PG8_BAR; PG8_MMA(1, 0, At, B0); PG8_MMA(1, 1, At, B1); PG8_BAR; PG8_SCHED;
	v_mfma_f32_16x16x32_bf16 v[60:63], v[128:131], v[194:197], 0
	v_mfma_f32_16x16x32_bf16 v[56:59], v[148:151], v[194:197], 0
	v_mfma_f32_16x16x32_bf16 v[44:47], v[128:131], v[202:205], 0
	v_mfma_f32_16x16x32_bf16 v[40:43], v[148:151], v[202:205], 0
	v_mfma_f32_16x16x32_bf16 v[28:31], v[128:131], v[210:213], 0
	v_mfma_f32_16x16x32_bf16 v[24:27], v[148:151], v[210:213], 0
	v_mfma_f32_16x16x32_bf16 v[12:15], v[128:131], v[234:237], 0
	v_mfma_f32_16x16x32_bf16 v[8:11], v[148:151], v[234:237], 0
	v_mfma_f32_16x16x32_bf16 v[60:63], v[144:147], v[198:201], v[60:63]
	v_mfma_f32_16x16x32_bf16 v[56:59], v[152:155], v[198:201], v[56:59]
	v_mfma_f32_16x16x32_bf16 v[44:47], v[144:147], v[206:209], v[44:47]
	v_mfma_f32_16x16x32_bf16 v[40:43], v[152:155], v[206:209], v[40:43]
	v_mfma_f32_16x16x32_bf16 v[28:31], v[144:147], v[230:233], v[28:31]
	v_mfma_f32_16x16x32_bf16 v[24:27], v[152:155], v[230:233], v[24:27]
	v_mfma_f32_16x16x32_bf16 v[12:15], v[144:147], v[238:241], v[12:15]
	v_mfma_f32_16x16x32_bf16 v[8:11], v[152:155], v[238:241], v[8:11]
	v_mfma_f32_16x16x32_bf16 v[52:55], v[156:159], v[194:197], 0
	v_mfma_f32_16x16x32_bf16 v[48:51], v[164:167], v[194:197], 0
	v_mfma_f32_16x16x32_bf16 v[36:39], v[156:159], v[202:205], 0
	v_mfma_f32_16x16x32_bf16 v[32:35], v[164:167], v[202:205], 0
	v_mfma_f32_16x16x32_bf16 v[20:23], v[156:159], v[210:213], 0
	v_mfma_f32_16x16x32_bf16 v[16:19], v[164:167], v[210:213], 0
	v_mfma_f32_16x16x32_bf16 v[4:7], v[156:159], v[234:237], 0
	v_mfma_f32_16x16x32_bf16 v[0:3], v[164:167], v[234:237], 0
	v_mfma_f32_16x16x32_bf16 v[52:55], v[160:163], v[198:201], v[52:55]
	v_mfma_f32_16x16x32_bf16 v[48:51], v[190:193], v[198:201], v[48:51]
	v_mfma_f32_16x16x32_bf16 v[36:39], v[160:163], v[206:209], v[36:39]
	v_mfma_f32_16x16x32_bf16 v[32:35], v[190:193], v[206:209], v[32:35]
	v_mfma_f32_16x16x32_bf16 v[20:23], v[160:163], v[230:233], v[20:23]
	v_mfma_f32_16x16x32_bf16 v[16:19], v[190:193], v[230:233], v[16:19]
	v_mfma_f32_16x16x32_bf16 v[4:7], v[160:163], v[238:241], v[4:7]
	v_mfma_f32_16x16x32_bf16 v[0:3], v[190:193], v[238:241], v[0:3]
	s_barrier
	s_add_i32 s2, 0, 0x18000
	s_add_i32 s24, 0, 0x1c000
	v_add_u32_e32 v152, s2, v184
	v_add_u32_e32 v190, s24, v184
	ds_read_b128 v[128:131], v152
	ds_read_b128 v[144:147], v152 offset:1024
	ds_read_b128 v[148:151], v152 offset:2048
	ds_read_b128 v[152:155], v152 offset:3072
	ds_read_b128 v[156:159], v190
	ds_read_b128 v[160:163], v190 offset:1024
	ds_read_b128 v[164:167], v190 offset:2048
	ds_read_b128 v[190:193], v190 offset:3072
	s_add_u32 s12, s16, 0x160000
	s_addc_u32 s13, s17, 0
	s_mov_b32 m0, s40
	v_lshl_add_u64 v[246:247], s[12:13], 0, v[138:139]
	ds_read_b128 v[194:197], v189 offset:32768
	ds_read_b128 v[198:201], v189 offset:33792
	ds_read_b128 v[202:205], v189 offset:34816
	ds_read_b128 v[206:209], v189 offset:35840
	ds_read_b128 v[210:213], v189 offset:36864
	ds_read_b128 v[230:233], v189 offset:37888
	ds_read_b128 v[234:237], v189 offset:38912
	ds_read_b128 v[238:241], v189 offset:39936
	global_load_lds_dwordx4 v[246:247], off
	v_lshl_add_u64 v[246:247], s[12:13], 0, v[134:135]
	s_mov_b32 m0, s41
	s_nop 0
	global_load_lds_dwordx4 v[246:247], off
	s_waitcnt vmcnt(8)
	s_waitcnt lgkmcnt(0)
	s_barrier
	v_mfma_f32_16x16x32_bf16 v[124:127], v[128:131], v[194:197], v[124:127]
	v_mfma_f32_16x16x32_bf16 v[120:123], v[148:151], v[194:197], v[120:123]
	v_mfma_f32_16x16x32_bf16 v[108:111], v[128:131], v[202:205], v[108:111]
	v_mfma_f32_16x16x32_bf16 v[104:107], v[148:151], v[202:205], v[104:107]
	v_mfma_f32_16x16x32_bf16 v[92:95], v[128:131], v[210:213], v[92:95]
	v_mfma_f32_16x16x32_bf16 v[88:91], v[148:151], v[210:213], v[88:91]
	v_mfma_f32_16x16x32_bf16 v[80:83], v[128:131], v[234:237], v[80:83]
	v_mfma_f32_16x16x32_bf16 v[72:75], v[148:151], v[234:237], v[72:75]
	v_mfma_f32_16x16x32_bf16 v[124:127], v[144:147], v[198:201], v[124:127]
	v_mfma_f32_16x16x32_bf16 v[120:123], v[152:155], v[198:201], v[120:123]
	v_mfma_f32_16x16x32_bf16 v[108:111], v[144:147], v[206:209], v[108:111]
	v_mfma_f32_16x16x32_bf16 v[104:107], v[152:155], v[206:209], v[104:107]
	v_mfma_f32_16x16x32_bf16 v[92:95], v[144:147], v[230:233], v[92:95]
	v_mfma_f32_16x16x32_bf16 v[88:91], v[152:155], v[230:233], v[88:91]
	v_mfma_f32_16x16x32_bf16 v[80:83], v[144:147], v[238:241], v[80:83]
	v_mfma_f32_16x16x32_bf16 v[72:75], v[152:155], v[238:241], v[72:75]
	v_mfma_f32_16x16x32_bf16 v[116:119], v[156:159], v[194:197], v[116:119]
	v_mfma_f32_16x16x32_bf16 v[112:115], v[164:167], v[194:197], v[112:115]
	v_mfma_f32_16x16x32_bf16 v[100:103], v[156:159], v[202:205], v[100:103]
	v_mfma_f32_16x16x32_bf16 v[96:99], v[164:167], v[202:205], v[96:99]
	v_mfma_f32_16x16x32_bf16 v[84:87], v[156:159], v[210:213], v[84:87]
	v_mfma_f32_16x16x32_bf16 v[76:79], v[164:167], v[210:213], v[76:79]
	v_mfma_f32_16x16x32_bf16 v[68:71], v[156:159], v[234:237], v[68:71]
	v_mfma_f32_16x16x32_bf16 v[64:67], v[164:167], v[234:237], v[64:67]
	v_mfma_f32_16x16x32_bf16 v[116:119], v[160:163], v[198:201], v[116:119]
	v_mfma_f32_16x16x32_bf16 v[112:115], v[190:193], v[198:201], v[112:115]
	v_mfma_f32_16x16x32_bf16 v[100:103], v[160:163], v[206:209], v[100:103]
	v_mfma_f32_16x16x32_bf16 v[96:99], v[190:193], v[206:209], v[96:99]
	v_mfma_f32_16x16x32_bf16 v[84:87], v[160:163], v[230:233], v[84:87]
	v_mfma_f32_16x16x32_bf16 v[76:79], v[190:193], v[230:233], v[76:79]
	v_mfma_f32_16x16x32_bf16 v[68:71], v[160:163], v[238:241], v[68:71]
	v_mfma_f32_16x16x32_bf16 v[64:67], v[190:193], v[238:241], v[64:67]
	s_barrier
; #define PG8_STAGE(bufoff, gbase, voff) do { _Pragma("unroll") for (int _i = 0; _i < 2; ++_i) \
;         __builtin_amdgcn_global_load_lds((const unsigned*)((const char*)(gbase) + (voff)[_i]), (LAS unsigned*)(lds + (bufoff) + ldsw + _i * 8192), 16, 0, 0); } while (0)
; #define PG8_LDA(dst, b, h) do { _Pragma("unroll") for (int m = 0; m < 4; ++m) _Pragma("unroll") for (int k = 0; k < 2; ++k) dst[m][k] = *(const LAS bf16x8*)(lds + PG8_SA(b, h) + aoff + m * 2048 + k * 1024); } while (0)
; #define PG8_WAIT_V(n) asm volatile("s_waitcnt vmcnt(" #n ")" ::: "memory")
; #define PG8_WAIT_L(n) asm volatile("s_waitcnt lgkmcnt(" #n ")" ::: "memory")
; template <class Epi>
; __device__ __forceinline__ void gemm_phase(LAS unsigned char* lds, const Gemm g, const StaticOrder& S, const Epi& E, const int tid) {
;     ...
;     for (;;) {
;         const bool has_next = S.next(ui + 1, nxt);
;         const char* nA = has_next ? PG8_APTR(nxt) : cA; const char* nB = has_next ? PG8_BPTR(nxt) : cB;
;         for (int t = 0; t < nt; t += 2) {
;             const bool last = (t == nt - 2);
;             const char* a1 = cA + (size_t)(t + 1) * kstep;
;             const char* a2 = last ? nA : cA + (size_t)(t + 2) * kstep; const char* b2 = last ? nB : cB + (size_t)(t + 2) * kstep;
;             const char* a3 = a2 + kstep; const char* b3 = b2 + kstep;
;             PG8_LDB(B0, 0, 0); PG8_LDB(B1, 0, 1); PG8_SCHED; PG8_LDA(At, 0, 0); PG8_STAGE(PG8_SA(1, 1), a1 + hsA, voffA);
;             PG8_WAIT_V(8); PG8_WAIT_L(0); PG8_BAR; PG8_MMA(0, 0, At, B0); PG8_MMA(0, 1, At, B1); PG8_BAR; PG8_SCHED;
;             PG8_LDA(At, 0, 1); PG8_STAGE(PG8_SB(0, 0), b2, voffB); PG8_STAGE(PG8_SB(0, 1), b2 + hsB, voffB); PG8_STAGE(PG8_SA(0, 0), a2, voffA);
;             PG8_WAIT_V(8); PG8_WAIT_L(0); PG8_BAR; PG8_MMA(1, 0, At, B0); PG8_MMA(1, 1, At, B1); PG8_BAR; PG8_SCHED;
;             PG8_LDB(B0, 1, 0); PG8_LDB(B1, 1, 1); PG8_SCHED; PG8_LDA(At, 1, 0); PG8_STAGE(PG8_SA(0, 1), a2 + hsA, voffA);
;             PG8_WAIT_V(8); PG8_WAIT_L(0); PG8_BAR; PG8_MMA(0, 0, At, B0); PG8_MMA(0, 1, At, B1); PG8_BAR; PG8_SCHED;
;             PG8_LDA(At, 1, 1); PG8_STAGE(PG8_SB(1, 0), b3, voffB); PG8_STAGE(PG8_SB(1, 1), b3 + hsB, voffB); PG8_STAGE(PG8_SA(1, 0), a3, voffA);
;             PG8_WAIT_V(8); PG8_WAIT_L(0); PG8_BAR; PG8_MMA(1, 0, At, B0); PG8_MMA(1, 1, At, B1); PG8_BAR; PG8_SCHED;
	s_add_i32 s2, s2, s27
	v_lshl_add_u64 v[170:171], v[170:171], 0, s[28:29]
	s_mov_b32 m0, s2
	ds_read_b128 v[194:197], v189 offset:49152
	ds_read_b128 v[198:201], v189 offset:50176
	ds_read_b128 v[202:205], v189 offset:51200
	ds_read_b128 v[206:209], v189 offset:52224
	ds_read_b128 v[210:213], v189 offset:53248
	ds_read_b128 v[230:233], v189 offset:54272
	ds_read_b128 v[234:237], v189 offset:55296
	ds_read_b128 v[238:241], v189 offset:56320
	global_load_lds_dwordx4 v[170:171], off
	s_add_i32 m0, s2, 0x2000
	s_add_u32 s12, s14, 0x160080
	v_lshl_add_u64 v[170:171], v[172:173], 0, s[28:29]
	s_addc_u32 s13, s15, 0
	s_add_i32 s2, s24, s27
	global_load_lds_dwordx4 v[170:171], off
	v_lshl_add_u64 v[170:171], s[12:13], 0, v[136:137]
	s_mov_b32 m0, s2
	s_nop 0
	global_load_lds_dwordx4 v[170:171], off
	v_lshl_add_u64 v[170:171], s[12:13], 0, v[132:133]
	s_add_i32 m0, s2, 0x2000
	s_nop 0
	global_load_lds_dwordx4 v[170:171], off
	v_lshl_add_u64 v[170:171], v[242:243], 0, s[28:29]
	s_mov_b32 m0, s44
	s_nop 0
	global_load_lds_dwordx4 v[170:171], off
	v_lshl_add_u64 v[170:171], v[244:245], 0, s[28:29]
	s_mov_b32 m0, s45
	s_nop 0
	global_load_lds_dwordx4 v[170:171], off
	s_waitcnt vmcnt(8)
	s_waitcnt lgkmcnt(0)
	s_barrier
	v_mfma_f32_16x16x32_bf16 v[60:63], v[128:131], v[194:197], v[60:63]
	v_mfma_f32_16x16x32_bf16 v[56:59], v[148:151], v[194:197], v[56:59]
	v_mfma_f32_16x16x32_bf16 v[44:47], v[128:131], v[202:205], v[44:47]
	v_mfma_f32_16x16x32_bf16 v[40:43], v[148:151], v[202:205], v[40:43]
	v_mfma_f32_16x16x32_bf16 v[28:31], v[128:131], v[210:213], v[28:31]
	v_mfma_f32_16x16x32_bf16 v[24:27], v[148:151], v[210:213], v[24:27]
	v_mfma_f32_16x16x32_bf16 v[12:15], v[128:131], v[234:237], v[12:15]
	v_mfma_f32_16x16x32_bf16 v[8:11], v[148:151], v[234:237], v[8:11]
	v_mfma_f32_16x16x32_bf16 v[60:63], v[144:147], v[198:201], v[60:63]
	v_mfma_f32_16x16x32_bf16 v[56:59], v[152:155], v[198:201], v[56:59]
	v_mfma_f32_16x16x32_bf16 v[44:47], v[144:147], v[206:209], v[44:47]
	v_mfma_f32_16x16x32_bf16 v[40:43], v[152:155], v[206:209], v[40:43]
	v_mfma_f32_16x16x32_bf16 v[28:31], v[144:147], v[230:233], v[28:31]
	v_mfma_f32_16x16x32_bf16 v[24:27], v[152:155], v[230:233], v[24:27]
	v_mfma_f32_16x16x32_bf16 v[12:15], v[144:147], v[238:241], v[12:15]
	v_mfma_f32_16x16x32_bf16 v[8:11], v[152:155], v[238:241], v[8:11]
	v_mfma_f32_16x16x32_bf16 v[52:55], v[156:159], v[194:197], v[52:55]
	v_mfma_f32_16x16x32_bf16 v[48:51], v[164:167], v[194:197], v[48:51]
	v_mfma_f32_16x16x32_bf16 v[36:39], v[156:159], v[202:205], v[36:39]
	v_mfma_f32_16x16x32_bf16 v[32:35], v[164:167], v[202:205], v[32:35]
	v_mfma_f32_16x16x32_bf16 v[20:23], v[156:159], v[210:213], v[20:23]
	v_mfma_f32_16x16x32_bf16 v[16:19], v[164:167], v[210:213], v[16:19]
	v_mfma_f32_16x16x32_bf16 v[4:7], v[156:159], v[234:237], v[4:7]
	v_mfma_f32_16x16x32_bf16 v[0:3], v[164:167], v[234:237], v[0:3]
	v_mfma_f32_16x16x32_bf16 v[52:55], v[160:163], v[198:201], v[52:55]
	v_mfma_f32_16x16x32_bf16 v[48:51], v[190:193], v[198:201], v[48:51]
	v_mfma_f32_16x16x32_bf16 v[36:39], v[160:163], v[206:209], v[36:39]
	v_mfma_f32_16x16x32_bf16 v[32:35], v[190:193], v[206:209], v[32:35]
	v_mfma_f32_16x16x32_bf16 v[20:23], v[160:163], v[230:233], v[20:23]
	v_mfma_f32_16x16x32_bf16 v[16:19], v[190:193], v[230:233], v[16:19]
	v_mfma_f32_16x16x32_bf16 v[4:7], v[160:163], v[238:241], v[4:7]
	v_mfma_f32_16x16x32_bf16 v[0:3], v[190:193], v[238:241], v[0:3]
	s_barrier
	s_add_i32 s53, s53, 2
	s_add_u32 s38, s38, 0x100
	s_addc_u32 s39, s39, 0
	s_cmpk_gt_u32 s53, 0x55
	s_mov_b64 s[12:13], s[0:1]
